# v24 with residual-epilogue waits counting younger stores as in-order (younger atomics still excluded)
# speedup vs baseline: 1.0032x; 1.0032x over previous
; __device__ __forceinline__ unsigned pk2(float lo, float hi) { const f32v2_t v = {lo, hi}; const bf16v2_t b = __builtin_convertvector(v, bf16v2_t); return __builtin_bit_cast(unsigned, b); }
; #define ST_OUT2(p, v) __builtin_nontemporal_store((v), (p))
;     __device__ __forceinline__ void operator()(AccRef acc, const Unit& u, int wr, int wc, int fr, int fq) const {
;         const int row0 = u.pm * BM + wr * 64 + fr, col0 = u.pn * BM + wc * 32 + 8 * fq;
; #pragma unroll
;         for (int ai = 0; ai < 2; ++ai)
; #pragma unroll
;             for (int m = 0; m < 4; ++m) {
;                 const int row = row0 + ai * HALF + m * 16;
;                 float ss = 0.f;
; #pragma unroll
;                 for (int bj = 0; bj < 2; ++bj) {
;                     const size_t off = (size_t)row * DM + col0 + bj * HALF;
;                     f32x4 x0 = *(const f32x4*)(xin + off), x1 = *(const f32x4*)(xin + off + 4);
;                     x0 = x0 + acc[ai][bj][m][0] * scale; x1 = x1 + acc[ai][bj][m][1] * scale;
;                     ST_OUT2((f32x4*)(xout + off), x0); ST_OUT2((f32x4*)(xout + off + 4), x1);
;                     u32x4 o; o.x = pk2(x0[0], x0[1]); o.y = pk2(x0[2], x0[3]); o.z = pk2(x1[0], x1[1]); o.w = pk2(x1[2], x1[3]);
;                     if (wxb) ST_OUT2((u32x4*)(XB + off), o);
;                     ss += x0[0] * x0[0] + x0[1] * x0[1] + x0[2] * x0[2] + x0[3] * x0[3] + x1[0] * x1[0] + x1[1] * x1[1] + x1[2] * x1[2] + x1[3] * x1[3];
;                 }
;                 ss += __shfl_xor(ss, 16); ss += __shfl_xor(ss, 32);
;                 if (fq == 0) atomicAdd(rssn + row, (unsigned long long)(ss * 16777216.f));
.LBB0_101:
	v_lshl_add_u32 v156, s20, 8, v164
	v_lshl_or_b32 v160, s60, 8, v166
	v_ashrrev_i32_e32 v157, 31, v156
	v_ashrrev_i32_e32 v161, 31, v160
	v_lshlrev_b64 v[158:159], 11, v[156:157]
	v_lshl_add_u64 v[158:159], v[158:159], 0, v[160:161]
	v_lshl_add_u64 v[194:195], v[158:159], 2, s[80:81]
	v_lshl_add_u64 v[196:197], v[158:159], 2, s[80:81]
	v_lshl_add_u64 v[198:199], v[158:159], 1, s[90:91]
	v_lshl_add_u64 v[200:201], v[156:157], 3, s[42:43]
	v_and_b32_e32 v204, 64, v177
	v_add_u32_e32 v204, 64, v204
	v_xor_b32_e32 v202, 16, v177
	v_xor_b32_e32 v203, 32, v177
	v_cmp_lt_i32_e32 vcc, v202, v204
	s_nop 1
	v_cndmask_b32_e32 v202, v177, v202, vcc
	v_cmp_lt_i32_e32 vcc, v203, v204
	s_nop 1
	v_cndmask_b32_e32 v203, v177, v203, vcc
	v_lshlrev_b32_e32 v202, 2, v202
	v_lshlrev_b32_e32 v203, 2, v203
	s_mov_b32 s101, 0
	s_mov_b32 s100, 0x0
	v_lshl_add_u64 v[204:205], v[194:195], 0, s[100:101]
	global_load_dwordx4 v[206:209], v[204:205], off
	global_load_dwordx4 v[210:213], v[204:205], off offset:16
	s_mov_b32 s100, 0x0
	v_lshl_add_u64 v[204:205], v[194:195], 0, s[100:101]
	global_load_dwordx4 v[214:217], v[204:205], off offset:512
	global_load_dwordx4 v[218:221], v[204:205], off offset:528
	s_mov_b32 s100, 0x20000
	v_lshl_add_u64 v[204:205], v[194:195], 0, s[100:101]
	global_load_dwordx4 v[222:225], v[204:205], off
	global_load_dwordx4 v[226:229], v[204:205], off offset:16
	s_mov_b32 s100, 0x20000
	v_lshl_add_u64 v[204:205], v[194:195], 0, s[100:101]
	global_load_dwordx4 v[230:233], v[204:205], off offset:512
	global_load_dwordx4 v[234:237], v[204:205], off offset:528
	s_waitcnt vmcnt(6)
	v_pk_add_f32 v[124:125], v[124:125], v[206:207]
	v_pk_add_f32 v[126:127], v[126:127], v[208:209]
	v_pk_add_f32 v[120:121], v[120:121], v[210:211]
	v_pk_add_f32 v[122:123], v[122:123], v[212:213]
	s_mov_b32 s100, 0x0
	v_lshl_add_u64 v[182:183], v[196:197], 0, s[100:101]
	global_store_dwordx4 v[182:183], v[124:127], off
	global_store_dwordx4 v[182:183], v[120:123], off offset:16
	v_cvt_pk_bf16_f32 v186, v124, v125
	v_cvt_pk_bf16_f32 v187, v126, v127
	v_cvt_pk_bf16_f32 v188, v120, v121
	v_cvt_pk_bf16_f32 v189, v122, v123
	s_mov_b32 s100, 0x0
	v_lshl_add_u64 v[184:185], v[198:199], 0, s[100:101]
	global_store_dwordx4 v[184:185], v[186:189], off
	v_mul_f32_e32 v170, v125, v125
	v_fmac_f32_e32 v170, v124, v124
	v_fmac_f32_e32 v170, v126, v126
	v_fmac_f32_e32 v170, v127, v127
	v_fmac_f32_e32 v170, v120, v120
	v_fmac_f32_e32 v170, v121, v121
	v_fmac_f32_e32 v170, v122, v122
	v_fmac_f32_e32 v170, v123, v123
	s_mov_b32 s100, 0x40000
	v_lshl_add_u64 v[204:205], v[194:195], 0, s[100:101]
	global_load_dwordx4 v[206:209], v[204:205], off
	global_load_dwordx4 v[210:213], v[204:205], off offset:16
	s_waitcnt vmcnt(9)
	v_pk_add_f32 v[116:117], v[116:117], v[214:215]
	v_pk_add_f32 v[118:119], v[118:119], v[216:217]
	v_pk_add_f32 v[112:113], v[112:113], v[218:219]
	v_pk_add_f32 v[114:115], v[114:115], v[220:221]
	s_mov_b32 s100, 0x0
	v_lshl_add_u64 v[182:183], v[196:197], 0, s[100:101]
	global_store_dwordx4 v[182:183], v[116:119], off offset:512
	global_store_dwordx4 v[182:183], v[112:115], off offset:528
	v_cvt_pk_bf16_f32 v186, v116, v117
	v_cvt_pk_bf16_f32 v187, v118, v119
	v_cvt_pk_bf16_f32 v188, v112, v113
	v_cvt_pk_bf16_f32 v189, v114, v115
	s_mov_b32 s100, 0x0
	v_lshl_add_u64 v[184:185], v[198:199], 0, s[100:101]
	global_store_dwordx4 v[184:185], v[186:189], off offset:256
	v_mul_f32_e32 v171, v117, v117
	v_fmac_f32_e32 v171, v116, v116
	v_fmac_f32_e32 v171, v118, v118
	v_fmac_f32_e32 v171, v119, v119
	v_fmac_f32_e32 v171, v112, v112
	v_fmac_f32_e32 v171, v113, v113
	v_fmac_f32_e32 v171, v114, v114
	v_fmac_f32_e32 v171, v115, v115
	v_add_f32_e32 v170, v170, v171
	ds_bpermute_b32 v163, v202, v170
	s_waitcnt lgkmcnt(0)
	v_add_f32_e32 v170, v170, v163
	ds_bpermute_b32 v163, v203, v170
	s_and_saveexec_b64 s[22:23], s[38:39]
	s_waitcnt lgkmcnt(0)
	v_add_f32_e32 v170, v170, v163
	v_mul_f32_e32 v170, 0x4b800000, v170
	v_trunc_f32_e32 v170, v170
	v_mul_f32_e32 v163, 0x2f800000, v170
	v_floor_f32_e32 v163, v163
	v_fmac_f32_e32 v170, 0xcf800000, v163
	v_cvt_u32_f32_e32 v172, v170
	v_cvt_u32_f32_e32 v173, v163
	s_mov_b32 s100, 0x0
	v_lshl_add_u64 v[184:185], v[200:201], 0, s[100:101]
	global_atomic_add_x2 v[184:185], v[172:173], off
	s_or_b64 exec, exec, s[22:23]
	s_mov_b32 s100, 0x40000
	v_lshl_add_u64 v[204:205], v[194:195], 0, s[100:101]
	global_load_dwordx4 v[214:217], v[204:205], off offset:512
	global_load_dwordx4 v[218:221], v[204:205], off offset:528
	s_waitcnt vmcnt(12)
	v_pk_add_f32 v[108:109], v[108:109], v[222:223]
	v_pk_add_f32 v[110:111], v[110:111], v[224:225]
	v_pk_add_f32 v[104:105], v[104:105], v[226:227]
	v_pk_add_f32 v[106:107], v[106:107], v[228:229]
	s_mov_b32 s100, 0x20000
	v_lshl_add_u64 v[182:183], v[196:197], 0, s[100:101]
	global_store_dwordx4 v[182:183], v[108:111], off
	global_store_dwordx4 v[182:183], v[104:107], off offset:16
	v_cvt_pk_bf16_f32 v186, v108, v109
	v_cvt_pk_bf16_f32 v187, v110, v111
	v_cvt_pk_bf16_f32 v188, v104, v105
	v_cvt_pk_bf16_f32 v189, v106, v107
	s_mov_b32 s100, 0x10000
	v_lshl_add_u64 v[184:185], v[198:199], 0, s[100:101]
	global_store_dwordx4 v[184:185], v[186:189], off
	v_mul_f32_e32 v170, v109, v109
	v_fmac_f32_e32 v170, v108, v108
	v_fmac_f32_e32 v170, v110, v110
	v_fmac_f32_e32 v170, v111, v111
	v_fmac_f32_e32 v170, v104, v104
	v_fmac_f32_e32 v170, v105, v105
	v_fmac_f32_e32 v170, v106, v106
	v_fmac_f32_e32 v170, v107, v107
	s_mov_b32 s100, 0x60000
	v_lshl_add_u64 v[204:205], v[194:195], 0, s[100:101]
	global_load_dwordx4 v[222:225], v[204:205], off
	global_load_dwordx4 v[226:229], v[204:205], off offset:16
	s_waitcnt vmcnt(15)
; __device__ __forceinline__ unsigned pk2(float lo, float hi) { const f32v2_t v = {lo, hi}; const bf16v2_t b = __builtin_convertvector(v, bf16v2_t); return __builtin_bit_cast(unsigned, b); }
; #define ST_OUT2(p, v) __builtin_nontemporal_store((v), (p))
;     __device__ __forceinline__ void operator()(AccRef acc, const Unit& u, int wr, int wc, int fr, int fq) const {
;         const int row0 = u.pm * BM + wr * 64 + fr, col0 = u.pn * BM + wc * 32 + 8 * fq;
; #pragma unroll
;         for (int ai = 0; ai < 2; ++ai)
; #pragma unroll
;             for (int m = 0; m < 4; ++m) {
;                 const int row = row0 + ai * HALF + m * 16;
;                 float ss = 0.f;
; #pragma unroll
;                 for (int bj = 0; bj < 2; ++bj) {
;                     const size_t off = (size_t)row * DM + col0 + bj * HALF;
;                     f32x4 x0 = *(const f32x4*)(xin + off), x1 = *(const f32x4*)(xin + off + 4);
;                     x0 = x0 + acc[ai][bj][m][0] * scale; x1 = x1 + acc[ai][bj][m][1] * scale;
;                     ST_OUT2((f32x4*)(xout + off), x0); ST_OUT2((f32x4*)(xout + off + 4), x1);
;                     u32x4 o; o.x = pk2(x0[0], x0[1]); o.y = pk2(x0[2], x0[3]); o.z = pk2(x1[0], x1[1]); o.w = pk2(x1[2], x1[3]);
;                     if (wxb) ST_OUT2((u32x4*)(XB + off), o);
;                     ss += x0[0] * x0[0] + x0[1] * x0[1] + x0[2] * x0[2] + x0[3] * x0[3] + x1[0] * x1[0] + x1[1] * x1[1] + x1[2] * x1[2] + x1[3] * x1[3];
;                 }
;                 ss += __shfl_xor(ss, 16); ss += __shfl_xor(ss, 32);
;                 if (fq == 0) atomicAdd(rssn + row, (unsigned long long)(ss * 16777216.f));
	v_pk_add_f32 v[100:101], v[100:101], v[230:231]
	v_pk_add_f32 v[102:103], v[102:103], v[232:233]
	v_pk_add_f32 v[96:97], v[96:97], v[234:235]
	v_pk_add_f32 v[98:99], v[98:99], v[236:237]
	s_mov_b32 s100, 0x20000
	v_lshl_add_u64 v[182:183], v[196:197], 0, s[100:101]
	global_store_dwordx4 v[182:183], v[100:103], off offset:512
	global_store_dwordx4 v[182:183], v[96:99], off offset:528
	v_cvt_pk_bf16_f32 v186, v100, v101
	v_cvt_pk_bf16_f32 v187, v102, v103
	v_cvt_pk_bf16_f32 v188, v96, v97
	v_cvt_pk_bf16_f32 v189, v98, v99
	s_mov_b32 s100, 0x10000
	v_lshl_add_u64 v[184:185], v[198:199], 0, s[100:101]
	global_store_dwordx4 v[184:185], v[186:189], off offset:256
	v_mul_f32_e32 v171, v101, v101
	v_fmac_f32_e32 v171, v100, v100
	v_fmac_f32_e32 v171, v102, v102
	v_fmac_f32_e32 v171, v103, v103
	v_fmac_f32_e32 v171, v96, v96
	v_fmac_f32_e32 v171, v97, v97
	v_fmac_f32_e32 v171, v98, v98
	v_fmac_f32_e32 v171, v99, v99
	v_add_f32_e32 v170, v170, v171
	ds_bpermute_b32 v163, v202, v170
	s_waitcnt lgkmcnt(0)
	v_add_f32_e32 v170, v170, v163
	ds_bpermute_b32 v163, v203, v170
	s_and_saveexec_b64 s[22:23], s[38:39]
	s_waitcnt lgkmcnt(0)
	v_add_f32_e32 v170, v170, v163
	v_mul_f32_e32 v170, 0x4b800000, v170
	v_trunc_f32_e32 v170, v170
	v_mul_f32_e32 v163, 0x2f800000, v170
	v_floor_f32_e32 v163, v163
	v_fmac_f32_e32 v170, 0xcf800000, v163
	v_cvt_u32_f32_e32 v172, v170
	v_cvt_u32_f32_e32 v173, v163
	s_mov_b32 s100, 0x80
	v_lshl_add_u64 v[184:185], v[200:201], 0, s[100:101]
	global_atomic_add_x2 v[184:185], v[172:173], off
	s_or_b64 exec, exec, s[22:23]
	s_mov_b32 s100, 0x60000
	v_lshl_add_u64 v[204:205], v[194:195], 0, s[100:101]
	global_load_dwordx4 v[230:233], v[204:205], off offset:512
	global_load_dwordx4 v[234:237], v[204:205], off offset:528
	s_waitcnt vmcnt(15)
	v_pk_add_f32 v[92:93], v[92:93], v[206:207]
	v_pk_add_f32 v[94:95], v[94:95], v[208:209]
	v_pk_add_f32 v[88:89], v[88:89], v[210:211]
	v_pk_add_f32 v[90:91], v[90:91], v[212:213]
	s_mov_b32 s100, 0x40000
	v_lshl_add_u64 v[182:183], v[196:197], 0, s[100:101]
	global_store_dwordx4 v[182:183], v[92:95], off
	global_store_dwordx4 v[182:183], v[88:91], off offset:16
	v_cvt_pk_bf16_f32 v186, v92, v93
	v_cvt_pk_bf16_f32 v187, v94, v95
	v_cvt_pk_bf16_f32 v188, v88, v89
	v_cvt_pk_bf16_f32 v189, v90, v91
	s_mov_b32 s100, 0x20000
	v_lshl_add_u64 v[184:185], v[198:199], 0, s[100:101]
	global_store_dwordx4 v[184:185], v[186:189], off
	v_mul_f32_e32 v170, v93, v93
	v_fmac_f32_e32 v170, v92, v92
	v_fmac_f32_e32 v170, v94, v94
	v_fmac_f32_e32 v170, v95, v95
	v_fmac_f32_e32 v170, v88, v88
	v_fmac_f32_e32 v170, v89, v89
	v_fmac_f32_e32 v170, v90, v90
	v_fmac_f32_e32 v170, v91, v91
	s_mov_b32 s100, 0x100000
	v_lshl_add_u64 v[204:205], v[194:195], 0, s[100:101]
	global_load_dwordx4 v[206:209], v[204:205], off
	global_load_dwordx4 v[210:213], v[204:205], off offset:16
	s_waitcnt vmcnt(15)
	v_pk_add_f32 v[84:85], v[84:85], v[214:215]
	v_pk_add_f32 v[86:87], v[86:87], v[216:217]
	v_pk_add_f32 v[80:81], v[80:81], v[218:219]
	v_pk_add_f32 v[82:83], v[82:83], v[220:221]
	s_mov_b32 s100, 0x40000
	v_lshl_add_u64 v[182:183], v[196:197], 0, s[100:101]
	global_store_dwordx4 v[182:183], v[84:87], off offset:512
	global_store_dwordx4 v[182:183], v[80:83], off offset:528
	v_cvt_pk_bf16_f32 v186, v84, v85
	v_cvt_pk_bf16_f32 v187, v86, v87
	v_cvt_pk_bf16_f32 v188, v80, v81
	v_cvt_pk_bf16_f32 v189, v82, v83
	s_mov_b32 s100, 0x20000
	v_lshl_add_u64 v[184:185], v[198:199], 0, s[100:101]
	global_store_dwordx4 v[184:185], v[186:189], off offset:256
	v_mul_f32_e32 v171, v85, v85
	v_fmac_f32_e32 v171, v84, v84
	v_fmac_f32_e32 v171, v86, v86
	v_fmac_f32_e32 v171, v87, v87
	v_fmac_f32_e32 v171, v80, v80
	v_fmac_f32_e32 v171, v81, v81
	v_fmac_f32_e32 v171, v82, v82
	v_fmac_f32_e32 v171, v83, v83
	v_add_f32_e32 v170, v170, v171
	ds_bpermute_b32 v163, v202, v170
	s_waitcnt lgkmcnt(0)
	v_add_f32_e32 v170, v170, v163
	ds_bpermute_b32 v163, v203, v170
	s_and_saveexec_b64 s[22:23], s[38:39]
	s_waitcnt lgkmcnt(0)
	v_add_f32_e32 v170, v170, v163
	v_mul_f32_e32 v170, 0x4b800000, v170
	v_trunc_f32_e32 v170, v170
	v_mul_f32_e32 v163, 0x2f800000, v170
	v_floor_f32_e32 v163, v163
	v_fmac_f32_e32 v170, 0xcf800000, v163
	v_cvt_u32_f32_e32 v172, v170
	v_cvt_u32_f32_e32 v173, v163
	s_mov_b32 s100, 0x100
	v_lshl_add_u64 v[184:185], v[200:201], 0, s[100:101]
	global_atomic_add_x2 v[184:185], v[172:173], off
	s_or_b64 exec, exec, s[22:23]
	s_mov_b32 s100, 0x100000
	v_lshl_add_u64 v[204:205], v[194:195], 0, s[100:101]
	global_load_dwordx4 v[214:217], v[204:205], off offset:512
	global_load_dwordx4 v[218:221], v[204:205], off offset:528
	s_waitcnt vmcnt(15)
	v_pk_add_f32 v[76:77], v[76:77], v[222:223]
	v_pk_add_f32 v[78:79], v[78:79], v[224:225]
	v_pk_add_f32 v[72:73], v[72:73], v[226:227]
	v_pk_add_f32 v[74:75], v[74:75], v[228:229]
	s_mov_b32 s100, 0x60000
	v_lshl_add_u64 v[182:183], v[196:197], 0, s[100:101]
	global_store_dwordx4 v[182:183], v[76:79], off
	global_store_dwordx4 v[182:183], v[72:75], off offset:16
	v_cvt_pk_bf16_f32 v186, v76, v77
	v_cvt_pk_bf16_f32 v187, v78, v79
	v_cvt_pk_bf16_f32 v188, v72, v73
	v_cvt_pk_bf16_f32 v189, v74, v75
	s_mov_b32 s100, 0x30000
	v_lshl_add_u64 v[184:185], v[198:199], 0, s[100:101]
	global_store_dwordx4 v[184:185], v[186:189], off
	v_mul_f32_e32 v170, v77, v77
	v_fmac_f32_e32 v170, v76, v76
	v_fmac_f32_e32 v170, v78, v78
	v_fmac_f32_e32 v170, v79, v79
	v_fmac_f32_e32 v170, v72, v72
	v_fmac_f32_e32 v170, v73, v73
	v_fmac_f32_e32 v170, v74, v74
	v_fmac_f32_e32 v170, v75, v75
	s_mov_b32 s100, 0x120000
	v_lshl_add_u64 v[204:205], v[194:195], 0, s[100:101]
	global_load_dwordx4 v[222:225], v[204:205], off
	global_load_dwordx4 v[226:229], v[204:205], off offset:16
	s_waitcnt vmcnt(15)
; __device__ __forceinline__ unsigned pk2(float lo, float hi) { const f32v2_t v = {lo, hi}; const bf16v2_t b = __builtin_convertvector(v, bf16v2_t); return __builtin_bit_cast(unsigned, b); }
; #define ST_OUT2(p, v) __builtin_nontemporal_store((v), (p))
;     __device__ __forceinline__ void operator()(AccRef acc, const Unit& u, int wr, int wc, int fr, int fq) const {
;         const int row0 = u.pm * BM + wr * 64 + fr, col0 = u.pn * BM + wc * 32 + 8 * fq;
; #pragma unroll
;         for (int ai = 0; ai < 2; ++ai)
; #pragma unroll
;             for (int m = 0; m < 4; ++m) {
;                 const int row = row0 + ai * HALF + m * 16;
;                 float ss = 0.f;
; #pragma unroll
;                 for (int bj = 0; bj < 2; ++bj) {
;                     const size_t off = (size_t)row * DM + col0 + bj * HALF;
;                     f32x4 x0 = *(const f32x4*)(xin + off), x1 = *(const f32x4*)(xin + off + 4);
;                     x0 = x0 + acc[ai][bj][m][0] * scale; x1 = x1 + acc[ai][bj][m][1] * scale;
;                     ST_OUT2((f32x4*)(xout + off), x0); ST_OUT2((f32x4*)(xout + off + 4), x1);
;                     u32x4 o; o.x = pk2(x0[0], x0[1]); o.y = pk2(x0[2], x0[3]); o.z = pk2(x1[0], x1[1]); o.w = pk2(x1[2], x1[3]);
;                     if (wxb) ST_OUT2((u32x4*)(XB + off), o);
;                     ss += x0[0] * x0[0] + x0[1] * x0[1] + x0[2] * x0[2] + x0[3] * x0[3] + x1[0] * x1[0] + x1[1] * x1[1] + x1[2] * x1[2] + x1[3] * x1[3];
;                 }
;                 ss += __shfl_xor(ss, 16); ss += __shfl_xor(ss, 32);
;                 if (fq == 0) atomicAdd(rssn + row, (unsigned long long)(ss * 16777216.f));
	v_pk_add_f32 v[68:69], v[68:69], v[230:231]
	v_pk_add_f32 v[70:71], v[70:71], v[232:233]
	v_pk_add_f32 v[64:65], v[64:65], v[234:235]
	v_pk_add_f32 v[66:67], v[66:67], v[236:237]
	s_mov_b32 s100, 0x60000
	v_lshl_add_u64 v[182:183], v[196:197], 0, s[100:101]
	global_store_dwordx4 v[182:183], v[68:71], off offset:512
	global_store_dwordx4 v[182:183], v[64:67], off offset:528
	v_cvt_pk_bf16_f32 v186, v68, v69
	v_cvt_pk_bf16_f32 v187, v70, v71
	v_cvt_pk_bf16_f32 v188, v64, v65
	v_cvt_pk_bf16_f32 v189, v66, v67
	s_mov_b32 s100, 0x30000
	v_lshl_add_u64 v[184:185], v[198:199], 0, s[100:101]
	global_store_dwordx4 v[184:185], v[186:189], off offset:256
	v_mul_f32_e32 v171, v69, v69
	v_fmac_f32_e32 v171, v68, v68
	v_fmac_f32_e32 v171, v70, v70
	v_fmac_f32_e32 v171, v71, v71
	v_fmac_f32_e32 v171, v64, v64
	v_fmac_f32_e32 v171, v65, v65
	v_fmac_f32_e32 v171, v66, v66
	v_fmac_f32_e32 v171, v67, v67
	v_add_f32_e32 v170, v170, v171
	ds_bpermute_b32 v163, v202, v170
	s_waitcnt lgkmcnt(0)
	v_add_f32_e32 v170, v170, v163
	ds_bpermute_b32 v163, v203, v170
	s_and_saveexec_b64 s[22:23], s[38:39]
	s_waitcnt lgkmcnt(0)
	v_add_f32_e32 v170, v170, v163
	v_mul_f32_e32 v170, 0x4b800000, v170
	v_trunc_f32_e32 v170, v170
	v_mul_f32_e32 v163, 0x2f800000, v170
	v_floor_f32_e32 v163, v163
	v_fmac_f32_e32 v170, 0xcf800000, v163
	v_cvt_u32_f32_e32 v172, v170
	v_cvt_u32_f32_e32 v173, v163
	s_mov_b32 s100, 0x180
	v_lshl_add_u64 v[184:185], v[200:201], 0, s[100:101]
	global_atomic_add_x2 v[184:185], v[172:173], off
	s_or_b64 exec, exec, s[22:23]
	s_mov_b32 s100, 0x120000
	v_lshl_add_u64 v[204:205], v[194:195], 0, s[100:101]
	global_load_dwordx4 v[230:233], v[204:205], off offset:512
	global_load_dwordx4 v[234:237], v[204:205], off offset:528
	s_waitcnt vmcnt(15)
	v_pk_add_f32 v[60:61], v[60:61], v[206:207]
	v_pk_add_f32 v[62:63], v[62:63], v[208:209]
	v_pk_add_f32 v[56:57], v[56:57], v[210:211]
	v_pk_add_f32 v[58:59], v[58:59], v[212:213]
	s_mov_b32 s100, 0x100000
	v_lshl_add_u64 v[182:183], v[196:197], 0, s[100:101]
	global_store_dwordx4 v[182:183], v[60:63], off
	global_store_dwordx4 v[182:183], v[56:59], off offset:16
	v_cvt_pk_bf16_f32 v186, v60, v61
	v_cvt_pk_bf16_f32 v187, v62, v63
	v_cvt_pk_bf16_f32 v188, v56, v57
	v_cvt_pk_bf16_f32 v189, v58, v59
	s_mov_b32 s100, 0x80000
	v_lshl_add_u64 v[184:185], v[198:199], 0, s[100:101]
	global_store_dwordx4 v[184:185], v[186:189], off
	v_mul_f32_e32 v170, v61, v61
	v_fmac_f32_e32 v170, v60, v60
	v_fmac_f32_e32 v170, v62, v62
	v_fmac_f32_e32 v170, v63, v63
	v_fmac_f32_e32 v170, v56, v56
	v_fmac_f32_e32 v170, v57, v57
	v_fmac_f32_e32 v170, v58, v58
	v_fmac_f32_e32 v170, v59, v59
	s_mov_b32 s100, 0x140000
	v_lshl_add_u64 v[204:205], v[194:195], 0, s[100:101]
	global_load_dwordx4 v[206:209], v[204:205], off
	global_load_dwordx4 v[210:213], v[204:205], off offset:16
	s_waitcnt vmcnt(15)
	v_pk_add_f32 v[52:53], v[52:53], v[214:215]
	v_pk_add_f32 v[54:55], v[54:55], v[216:217]
	v_pk_add_f32 v[48:49], v[48:49], v[218:219]
	v_pk_add_f32 v[50:51], v[50:51], v[220:221]
	s_mov_b32 s100, 0x100000
	v_lshl_add_u64 v[182:183], v[196:197], 0, s[100:101]
	global_store_dwordx4 v[182:183], v[52:55], off offset:512
	global_store_dwordx4 v[182:183], v[48:51], off offset:528
	v_cvt_pk_bf16_f32 v186, v52, v53
	v_cvt_pk_bf16_f32 v187, v54, v55
	v_cvt_pk_bf16_f32 v188, v48, v49
	v_cvt_pk_bf16_f32 v189, v50, v51
	s_mov_b32 s100, 0x80000
	v_lshl_add_u64 v[184:185], v[198:199], 0, s[100:101]
	global_store_dwordx4 v[184:185], v[186:189], off offset:256
	v_mul_f32_e32 v171, v53, v53
	v_fmac_f32_e32 v171, v52, v52
	v_fmac_f32_e32 v171, v54, v54
	v_fmac_f32_e32 v171, v55, v55
	v_fmac_f32_e32 v171, v48, v48
	v_fmac_f32_e32 v171, v49, v49
	v_fmac_f32_e32 v171, v50, v50
	v_fmac_f32_e32 v171, v51, v51
	v_add_f32_e32 v170, v170, v171
	ds_bpermute_b32 v163, v202, v170
	s_waitcnt lgkmcnt(0)
	v_add_f32_e32 v170, v170, v163
	ds_bpermute_b32 v163, v203, v170
	s_and_saveexec_b64 s[22:23], s[38:39]
	s_waitcnt lgkmcnt(0)
	v_add_f32_e32 v170, v170, v163
	v_mul_f32_e32 v170, 0x4b800000, v170
	v_trunc_f32_e32 v170, v170
	v_mul_f32_e32 v163, 0x2f800000, v170
	v_floor_f32_e32 v163, v163
	v_fmac_f32_e32 v170, 0xcf800000, v163
	v_cvt_u32_f32_e32 v172, v170
	v_cvt_u32_f32_e32 v173, v163
	s_mov_b32 s100, 0x400
	v_lshl_add_u64 v[184:185], v[200:201], 0, s[100:101]
	global_atomic_add_x2 v[184:185], v[172:173], off
	s_or_b64 exec, exec, s[22:23]
	s_mov_b32 s100, 0x140000
	v_lshl_add_u64 v[204:205], v[194:195], 0, s[100:101]
	global_load_dwordx4 v[214:217], v[204:205], off offset:512
	global_load_dwordx4 v[218:221], v[204:205], off offset:528
	s_waitcnt vmcnt(15)
	v_pk_add_f32 v[44:45], v[44:45], v[222:223]
	v_pk_add_f32 v[46:47], v[46:47], v[224:225]
	v_pk_add_f32 v[40:41], v[40:41], v[226:227]
	v_pk_add_f32 v[42:43], v[42:43], v[228:229]
	s_mov_b32 s100, 0x120000
	v_lshl_add_u64 v[182:183], v[196:197], 0, s[100:101]
	global_store_dwordx4 v[182:183], v[44:47], off
	global_store_dwordx4 v[182:183], v[40:43], off offset:16
	v_cvt_pk_bf16_f32 v186, v44, v45
	v_cvt_pk_bf16_f32 v187, v46, v47
	v_cvt_pk_bf16_f32 v188, v40, v41
	v_cvt_pk_bf16_f32 v189, v42, v43
	s_mov_b32 s100, 0x90000
	v_lshl_add_u64 v[184:185], v[198:199], 0, s[100:101]
	global_store_dwordx4 v[184:185], v[186:189], off
	v_mul_f32_e32 v170, v45, v45
	v_fmac_f32_e32 v170, v44, v44
	v_fmac_f32_e32 v170, v46, v46
	v_fmac_f32_e32 v170, v47, v47
	v_fmac_f32_e32 v170, v40, v40
	v_fmac_f32_e32 v170, v41, v41
	v_fmac_f32_e32 v170, v42, v42
	v_fmac_f32_e32 v170, v43, v43
	s_mov_b32 s100, 0x160000
	v_lshl_add_u64 v[204:205], v[194:195], 0, s[100:101]
	global_load_dwordx4 v[222:225], v[204:205], off
	global_load_dwordx4 v[226:229], v[204:205], off offset:16
	s_waitcnt vmcnt(15)
; __device__ __forceinline__ unsigned pk2(float lo, float hi) { const f32v2_t v = {lo, hi}; const bf16v2_t b = __builtin_convertvector(v, bf16v2_t); return __builtin_bit_cast(unsigned, b); }
; #define ST_OUT2(p, v) __builtin_nontemporal_store((v), (p))
; #define PG8_BAR __builtin_amdgcn_s_barrier()
; template <class Epi, class Sched>
; __device__ __forceinline__ void gemm_phase(LAS unsigned char* lds, const Gemm g, const Sched& S, const Epi& E) {
;     ...
;         if (!has_next) break;
; #pragma unroll
;         for (int a = 0; a < 2; ++a)
; #pragma unroll
;             for (int b = 0; b < 2; ++b)
; #pragma unroll
;                 for (int m = 0; m < 4; ++m)
; #pragma unroll
;                     for (int n = 0; n < 2; ++n) acc[a][b][m][n] = (f32x4){0.f, 0.f, 0.f, 0.f};
;         cur = nxt; cA = nA; cB = nB; ++ui;
;         if (Sched::SEGMENTED) nt = S.nt(cur);
;     ...
;         if (wr == 1) PG8_BAR;
;     __device__ __forceinline__ void operator()(AccRef acc, const Unit& u, int wr, int wc, int fr, int fq) const {
;         const int row0 = u.pm * BM + wr * 64 + fr, col0 = u.pn * BM + wc * 32 + 8 * fq;
; #pragma unroll
;         for (int ai = 0; ai < 2; ++ai)
; #pragma unroll
;             for (int m = 0; m < 4; ++m) {
;                 const int row = row0 + ai * HALF + m * 16;
;                 float ss = 0.f;
; #pragma unroll
;                 for (int bj = 0; bj < 2; ++bj) {
;                     const size_t off = (size_t)row * DM + col0 + bj * HALF;
;                     f32x4 x0 = *(const f32x4*)(xin + off), x1 = *(const f32x4*)(xin + off + 4);
;                     x0 = x0 + acc[ai][bj][m][0] * scale; x1 = x1 + acc[ai][bj][m][1] * scale;
;                     ST_OUT2((f32x4*)(xout + off), x0); ST_OUT2((f32x4*)(xout + off + 4), x1);
;                     u32x4 o; o.x = pk2(x0[0], x0[1]); o.y = pk2(x0[2], x0[3]); o.z = pk2(x1[0], x1[1]); o.w = pk2(x1[2], x1[3]);
;                     if (wxb) ST_OUT2((u32x4*)(XB + off), o);
;                     ss += x0[0] * x0[0] + x0[1] * x0[1] + x0[2] * x0[2] + x0[3] * x0[3] + x1[0] * x1[0] + x1[1] * x1[1] + x1[2] * x1[2] + x1[3] * x1[3];
;                 }
;                 ss += __shfl_xor(ss, 16); ss += __shfl_xor(ss, 32);
;                 if (fq == 0) atomicAdd(rssn + row, (unsigned long long)(ss * 16777216.f));
	v_pk_add_f32 v[36:37], v[36:37], v[230:231]
	v_pk_add_f32 v[38:39], v[38:39], v[232:233]
	v_pk_add_f32 v[32:33], v[32:33], v[234:235]
	v_pk_add_f32 v[34:35], v[34:35], v[236:237]
	s_mov_b32 s100, 0x120000
	v_lshl_add_u64 v[182:183], v[196:197], 0, s[100:101]
	global_store_dwordx4 v[182:183], v[36:39], off offset:512
	global_store_dwordx4 v[182:183], v[32:35], off offset:528
	v_cvt_pk_bf16_f32 v186, v36, v37
	v_cvt_pk_bf16_f32 v187, v38, v39
	v_cvt_pk_bf16_f32 v188, v32, v33
	v_cvt_pk_bf16_f32 v189, v34, v35
	s_mov_b32 s100, 0x90000
	v_lshl_add_u64 v[184:185], v[198:199], 0, s[100:101]
	global_store_dwordx4 v[184:185], v[186:189], off offset:256
	v_mul_f32_e32 v171, v37, v37
	v_fmac_f32_e32 v171, v36, v36
	v_fmac_f32_e32 v171, v38, v38
	v_fmac_f32_e32 v171, v39, v39
	v_fmac_f32_e32 v171, v32, v32
	v_fmac_f32_e32 v171, v33, v33
	v_fmac_f32_e32 v171, v34, v34
	v_fmac_f32_e32 v171, v35, v35
	v_add_f32_e32 v170, v170, v171
	ds_bpermute_b32 v163, v202, v170
	s_waitcnt lgkmcnt(0)
	v_add_f32_e32 v170, v170, v163
	ds_bpermute_b32 v163, v203, v170
	s_and_saveexec_b64 s[22:23], s[38:39]
	s_waitcnt lgkmcnt(0)
	v_add_f32_e32 v170, v170, v163
	v_mul_f32_e32 v170, 0x4b800000, v170
	v_trunc_f32_e32 v170, v170
	v_mul_f32_e32 v163, 0x2f800000, v170
	v_floor_f32_e32 v163, v163
	v_fmac_f32_e32 v170, 0xcf800000, v163
	v_cvt_u32_f32_e32 v172, v170
	v_cvt_u32_f32_e32 v173, v163
	s_mov_b32 s100, 0x480
	v_lshl_add_u64 v[184:185], v[200:201], 0, s[100:101]
	global_atomic_add_x2 v[184:185], v[172:173], off
	s_or_b64 exec, exec, s[22:23]
	s_mov_b32 s100, 0x160000
	v_lshl_add_u64 v[204:205], v[194:195], 0, s[100:101]
	global_load_dwordx4 v[230:233], v[204:205], off offset:512
	global_load_dwordx4 v[234:237], v[204:205], off offset:528
	s_waitcnt vmcnt(15)
	v_pk_add_f32 v[28:29], v[28:29], v[206:207]
	v_pk_add_f32 v[30:31], v[30:31], v[208:209]
	v_pk_add_f32 v[24:25], v[24:25], v[210:211]
	v_pk_add_f32 v[26:27], v[26:27], v[212:213]
	s_mov_b32 s100, 0x140000
	v_lshl_add_u64 v[182:183], v[196:197], 0, s[100:101]
	global_store_dwordx4 v[182:183], v[28:31], off
	global_store_dwordx4 v[182:183], v[24:27], off offset:16
	v_cvt_pk_bf16_f32 v186, v28, v29
	v_cvt_pk_bf16_f32 v187, v30, v31
	v_cvt_pk_bf16_f32 v188, v24, v25
	v_cvt_pk_bf16_f32 v189, v26, v27
	s_mov_b32 s100, 0xa0000
	v_lshl_add_u64 v[184:185], v[198:199], 0, s[100:101]
	global_store_dwordx4 v[184:185], v[186:189], off
	v_mul_f32_e32 v170, v29, v29
	v_fmac_f32_e32 v170, v28, v28
	v_fmac_f32_e32 v170, v30, v30
	v_fmac_f32_e32 v170, v31, v31
	v_fmac_f32_e32 v170, v24, v24
	v_fmac_f32_e32 v170, v25, v25
	v_fmac_f32_e32 v170, v26, v26
	v_fmac_f32_e32 v170, v27, v27
	s_waitcnt vmcnt(13)
	v_pk_add_f32 v[20:21], v[20:21], v[214:215]
	v_pk_add_f32 v[22:23], v[22:23], v[216:217]
	v_pk_add_f32 v[16:17], v[16:17], v[218:219]
	v_pk_add_f32 v[18:19], v[18:19], v[220:221]
	s_mov_b32 s100, 0x140000
	v_lshl_add_u64 v[182:183], v[196:197], 0, s[100:101]
	global_store_dwordx4 v[182:183], v[20:23], off offset:512
	global_store_dwordx4 v[182:183], v[16:19], off offset:528
	v_cvt_pk_bf16_f32 v186, v20, v21
	v_cvt_pk_bf16_f32 v187, v22, v23
	v_cvt_pk_bf16_f32 v188, v16, v17
	v_cvt_pk_bf16_f32 v189, v18, v19
	s_mov_b32 s100, 0xa0000
	v_lshl_add_u64 v[184:185], v[198:199], 0, s[100:101]
	global_store_dwordx4 v[184:185], v[186:189], off offset:256
	v_mul_f32_e32 v171, v21, v21
	v_fmac_f32_e32 v171, v20, v20
	v_fmac_f32_e32 v171, v22, v22
	v_fmac_f32_e32 v171, v23, v23
	v_fmac_f32_e32 v171, v16, v16
	v_fmac_f32_e32 v171, v17, v17
	v_fmac_f32_e32 v171, v18, v18
	v_fmac_f32_e32 v171, v19, v19
	v_add_f32_e32 v170, v170, v171
	ds_bpermute_b32 v163, v202, v170
	s_waitcnt lgkmcnt(0)
	v_add_f32_e32 v170, v170, v163
	ds_bpermute_b32 v163, v203, v170
	s_and_saveexec_b64 s[22:23], s[38:39]
	s_waitcnt lgkmcnt(0)
	v_add_f32_e32 v170, v170, v163
	v_mul_f32_e32 v170, 0x4b800000, v170
	v_trunc_f32_e32 v170, v170
	v_mul_f32_e32 v163, 0x2f800000, v170
	v_floor_f32_e32 v163, v163
	v_fmac_f32_e32 v170, 0xcf800000, v163
	v_cvt_u32_f32_e32 v172, v170
	v_cvt_u32_f32_e32 v173, v163
	s_mov_b32 s100, 0x500
	v_lshl_add_u64 v[184:185], v[200:201], 0, s[100:101]
	global_atomic_add_x2 v[184:185], v[172:173], off
	s_or_b64 exec, exec, s[22:23]
	s_waitcnt vmcnt(11)
	v_pk_add_f32 v[12:13], v[12:13], v[222:223]
	v_pk_add_f32 v[14:15], v[14:15], v[224:225]
	v_pk_add_f32 v[8:9], v[8:9], v[226:227]
	v_pk_add_f32 v[10:11], v[10:11], v[228:229]
	s_mov_b32 s100, 0x160000
	v_lshl_add_u64 v[182:183], v[196:197], 0, s[100:101]
	global_store_dwordx4 v[182:183], v[12:15], off
	global_store_dwordx4 v[182:183], v[8:11], off offset:16
	v_cvt_pk_bf16_f32 v186, v12, v13
	v_cvt_pk_bf16_f32 v187, v14, v15
	v_cvt_pk_bf16_f32 v188, v8, v9
	v_cvt_pk_bf16_f32 v189, v10, v11
	s_mov_b32 s100, 0xb0000
	v_lshl_add_u64 v[184:185], v[198:199], 0, s[100:101]
	global_store_dwordx4 v[184:185], v[186:189], off
	v_mul_f32_e32 v170, v13, v13
	v_fmac_f32_e32 v170, v12, v12
	v_fmac_f32_e32 v170, v14, v14
	v_fmac_f32_e32 v170, v15, v15
	v_fmac_f32_e32 v170, v8, v8
	v_fmac_f32_e32 v170, v9, v9
	v_fmac_f32_e32 v170, v10, v10
	v_fmac_f32_e32 v170, v11, v11
	s_waitcnt vmcnt(9)
	v_pk_add_f32 v[4:5], v[4:5], v[230:231]
	v_pk_add_f32 v[6:7], v[6:7], v[232:233]
	v_pk_add_f32 v[0:1], v[0:1], v[234:235]
	v_pk_add_f32 v[2:3], v[2:3], v[236:237]
	s_mov_b32 s100, 0x160000
	v_lshl_add_u64 v[182:183], v[196:197], 0, s[100:101]
	global_store_dwordx4 v[182:183], v[4:7], off offset:512
	global_store_dwordx4 v[182:183], v[0:3], off offset:528
	v_cvt_pk_bf16_f32 v186, v4, v5
	v_cvt_pk_bf16_f32 v187, v6, v7
	v_cvt_pk_bf16_f32 v188, v0, v1
	v_cvt_pk_bf16_f32 v189, v2, v3
	s_mov_b32 s100, 0xb0000
	v_lshl_add_u64 v[184:185], v[198:199], 0, s[100:101]
	global_store_dwordx4 v[184:185], v[186:189], off offset:256
	v_mul_f32_e32 v171, v5, v5
	v_fmac_f32_e32 v171, v4, v4
	v_fmac_f32_e32 v171, v6, v6
	v_fmac_f32_e32 v171, v7, v7
	v_fmac_f32_e32 v171, v0, v0
	v_fmac_f32_e32 v171, v1, v1
	v_fmac_f32_e32 v171, v2, v2
	v_fmac_f32_e32 v171, v3, v3
	v_add_f32_e32 v170, v170, v171
	ds_bpermute_b32 v163, v202, v170
	s_waitcnt lgkmcnt(0)
	v_add_f32_e32 v170, v170, v163
	ds_bpermute_b32 v163, v203, v170
	s_and_saveexec_b64 s[22:23], s[38:39]
	s_waitcnt lgkmcnt(0)
	v_add_f32_e32 v170, v170, v163
	v_mul_f32_e32 v170, 0x4b800000, v170
	v_trunc_f32_e32 v170, v170
	v_mul_f32_e32 v163, 0x2f800000, v170
	v_floor_f32_e32 v163, v163
	v_fmac_f32_e32 v170, 0xcf800000, v163
	v_cvt_u32_f32_e32 v172, v170
	v_cvt_u32_f32_e32 v173, v163
	s_mov_b32 s100, 0x580
	v_lshl_add_u64 v[184:185], v[200:201], 0, s[100:101]
	global_atomic_add_x2 v[184:185], v[172:173], off
	s_or_b64 exec, exec, s[22:23]
	s_movk_i32 s92, 0x37ff
	s_mov_b64 s[16:17], 0x58000
	s_andn2_b64 vcc, exec, s[40:41]
	s_mov_b64 s[22:23], -1
	s_cbranch_vccnz .LBB0_90
	s_andn2_b64 vcc, exec, s[0:1]
	s_cbranch_vccnz .LBB0_89
	s_barrier
	s_branch .LBB0_89

; __device__ __forceinline__ unsigned pk2(float lo, float hi) { const f32v2_t v = {lo, hi}; const bf16v2_t b = __builtin_convertvector(v, bf16v2_t); return __builtin_bit_cast(unsigned, b); }
; #define ST_OUT2(p, v) __builtin_nontemporal_store((v), (p))
;     __device__ __forceinline__ void operator()(AccRef acc, const Unit& u, int wr, int wc, int fr, int fq) const {
;         const int row0 = u.pm * BM + wr * 64 + fr, col0 = u.pn * BM + wc * 32 + 8 * fq;
; #pragma unroll
;         for (int ai = 0; ai < 2; ++ai)
; #pragma unroll
;             for (int m = 0; m < 4; ++m) {
;                 const int row = row0 + ai * HALF + m * 16;
;                 float ss = 0.f;
; #pragma unroll
;                 for (int bj = 0; bj < 2; ++bj) {
;                     const size_t off = (size_t)row * DM + col0 + bj * HALF;
;                     f32x4 x0 = *(const f32x4*)(xin + off), x1 = *(const f32x4*)(xin + off + 4);
;                     x0 = x0 + acc[ai][bj][m][0] * scale; x1 = x1 + acc[ai][bj][m][1] * scale;
;                     ST_OUT2((f32x4*)(xout + off), x0); ST_OUT2((f32x4*)(xout + off + 4), x1);
;                     u32x4 o; o.x = pk2(x0[0], x0[1]); o.y = pk2(x0[2], x0[3]); o.z = pk2(x1[0], x1[1]); o.w = pk2(x1[2], x1[3]);
;                     if (wxb) ST_OUT2((u32x4*)(XB + off), o);
;                     ss += x0[0] * x0[0] + x0[1] * x0[1] + x0[2] * x0[2] + x0[3] * x0[3] + x1[0] * x1[0] + x1[1] * x1[1] + x1[2] * x1[2] + x1[3] * x1[3];
;                 }
;                 ss += __shfl_xor(ss, 16); ss += __shfl_xor(ss, 32);
;                 if (fq == 0) atomicAdd(rssn + row, (unsigned long long)(ss * 16777216.f));
.LBB0_682:
	v_lshl_add_u32 v156, s61, 8, v166
	v_lshl_or_b32 v160, s60, 8, v168
	v_ashrrev_i32_e32 v157, 31, v156
	v_ashrrev_i32_e32 v161, 31, v160
	v_lshlrev_b64 v[158:159], 11, v[156:157]
	v_lshl_add_u64 v[158:159], v[158:159], 0, v[160:161]
	v_lshl_add_u64 v[194:195], v[158:159], 2, s[44:45]
	v_lshl_add_u64 v[196:197], v[158:159], 2, s[80:81]
	v_lshl_add_u64 v[198:199], v[158:159], 1, s[90:91]
	v_lshl_add_u64 v[200:201], v[156:157], 3, s[46:47]
	v_and_b32_e32 v204, 64, v177
	v_add_u32_e32 v204, 64, v204
	v_xor_b32_e32 v202, 16, v177
	v_xor_b32_e32 v203, 32, v177
	v_cmp_lt_i32_e32 vcc, v202, v204
	s_nop 1
	v_cndmask_b32_e32 v202, v177, v202, vcc
	v_cmp_lt_i32_e32 vcc, v203, v204
	s_nop 1
	v_cndmask_b32_e32 v203, v177, v203, vcc
	v_lshlrev_b32_e32 v202, 2, v202
	v_lshlrev_b32_e32 v203, 2, v203
	s_mov_b32 s101, 0
	s_and_b64 vcc, exec, s[48:49]
	s_cbranch_vccz .Lrs2_nowxb
	s_mov_b32 s100, 0x0
	v_lshl_add_u64 v[204:205], v[194:195], 0, s[100:101]
	global_load_dwordx4 v[206:209], v[204:205], off
	global_load_dwordx4 v[210:213], v[204:205], off offset:16
	s_mov_b32 s100, 0x0
	v_lshl_add_u64 v[204:205], v[194:195], 0, s[100:101]
	global_load_dwordx4 v[214:217], v[204:205], off offset:512
	global_load_dwordx4 v[218:221], v[204:205], off offset:528
	s_mov_b32 s100, 0x20000
	v_lshl_add_u64 v[204:205], v[194:195], 0, s[100:101]
	global_load_dwordx4 v[222:225], v[204:205], off
	global_load_dwordx4 v[226:229], v[204:205], off offset:16
	s_mov_b32 s100, 0x20000
	v_lshl_add_u64 v[204:205], v[194:195], 0, s[100:101]
	global_load_dwordx4 v[230:233], v[204:205], off offset:512
	global_load_dwordx4 v[234:237], v[204:205], off offset:528
	s_waitcnt vmcnt(6)
	v_pk_fma_f32 v[124:125], v[124:125], 0.5, v[206:207] op_sel_hi:[1,0,1]
	v_pk_fma_f32 v[126:127], v[126:127], 0.5, v[208:209] op_sel_hi:[1,0,1]
	v_pk_fma_f32 v[120:121], v[120:121], 0.5, v[210:211] op_sel_hi:[1,0,1]
	v_pk_fma_f32 v[122:123], v[122:123], 0.5, v[212:213] op_sel_hi:[1,0,1]
	s_mov_b32 s100, 0x0
	v_lshl_add_u64 v[182:183], v[196:197], 0, s[100:101]
	global_store_dwordx4 v[182:183], v[124:127], off
	global_store_dwordx4 v[182:183], v[120:123], off offset:16
	v_cvt_pk_bf16_f32 v186, v124, v125
	v_cvt_pk_bf16_f32 v187, v126, v127
	v_cvt_pk_bf16_f32 v188, v120, v121
	v_cvt_pk_bf16_f32 v189, v122, v123
	s_mov_b32 s100, 0x0
	v_lshl_add_u64 v[184:185], v[198:199], 0, s[100:101]
	global_store_dwordx4 v[184:185], v[186:189], off
	v_mul_f32_e32 v170, v125, v125
	v_fmac_f32_e32 v170, v124, v124
	v_fmac_f32_e32 v170, v126, v126
	v_fmac_f32_e32 v170, v127, v127
	v_fmac_f32_e32 v170, v120, v120
	v_fmac_f32_e32 v170, v121, v121
	v_fmac_f32_e32 v170, v122, v122
	v_fmac_f32_e32 v170, v123, v123
	s_mov_b32 s100, 0x40000
	v_lshl_add_u64 v[204:205], v[194:195], 0, s[100:101]
	global_load_dwordx4 v[206:209], v[204:205], off
	global_load_dwordx4 v[210:213], v[204:205], off offset:16
	s_waitcnt vmcnt(9)
	v_pk_fma_f32 v[116:117], v[116:117], 0.5, v[214:215] op_sel_hi:[1,0,1]
	v_pk_fma_f32 v[118:119], v[118:119], 0.5, v[216:217] op_sel_hi:[1,0,1]
	v_pk_fma_f32 v[112:113], v[112:113], 0.5, v[218:219] op_sel_hi:[1,0,1]
	v_pk_fma_f32 v[114:115], v[114:115], 0.5, v[220:221] op_sel_hi:[1,0,1]
	s_mov_b32 s100, 0x0
	v_lshl_add_u64 v[182:183], v[196:197], 0, s[100:101]
	global_store_dwordx4 v[182:183], v[116:119], off offset:512
	global_store_dwordx4 v[182:183], v[112:115], off offset:528
	v_cvt_pk_bf16_f32 v186, v116, v117
	v_cvt_pk_bf16_f32 v187, v118, v119
	v_cvt_pk_bf16_f32 v188, v112, v113
	v_cvt_pk_bf16_f32 v189, v114, v115
	s_mov_b32 s100, 0x0
	v_lshl_add_u64 v[184:185], v[198:199], 0, s[100:101]
	global_store_dwordx4 v[184:185], v[186:189], off offset:256
	v_mul_f32_e32 v171, v117, v117
	v_fmac_f32_e32 v171, v116, v116
	v_fmac_f32_e32 v171, v118, v118
	v_fmac_f32_e32 v171, v119, v119
	v_fmac_f32_e32 v171, v112, v112
	v_fmac_f32_e32 v171, v113, v113
	v_fmac_f32_e32 v171, v114, v114
	v_fmac_f32_e32 v171, v115, v115
	v_add_f32_e32 v170, v170, v171
	ds_bpermute_b32 v163, v202, v170
	s_waitcnt lgkmcnt(0)
	v_add_f32_e32 v170, v170, v163
	ds_bpermute_b32 v163, v203, v170
	s_and_saveexec_b64 s[54:55], s[38:39]
	s_waitcnt lgkmcnt(0)
	v_add_f32_e32 v170, v170, v163
	v_mul_f32_e32 v170, 0x4b800000, v170
	v_trunc_f32_e32 v170, v170
	v_mul_f32_e32 v163, 0x2f800000, v170
	v_floor_f32_e32 v163, v163
	v_fmac_f32_e32 v170, 0xcf800000, v163
	v_cvt_u32_f32_e32 v172, v170
	v_cvt_u32_f32_e32 v173, v163
	s_mov_b32 s100, 0x0
	v_lshl_add_u64 v[184:185], v[200:201], 0, s[100:101]
	global_atomic_add_x2 v[184:185], v[172:173], off
	s_or_b64 exec, exec, s[54:55]
	s_mov_b32 s100, 0x40000
	v_lshl_add_u64 v[204:205], v[194:195], 0, s[100:101]
	global_load_dwordx4 v[214:217], v[204:205], off offset:512
	global_load_dwordx4 v[218:221], v[204:205], off offset:528
	s_waitcnt vmcnt(12)
	v_pk_fma_f32 v[108:109], v[108:109], 0.5, v[222:223] op_sel_hi:[1,0,1]
	v_pk_fma_f32 v[110:111], v[110:111], 0.5, v[224:225] op_sel_hi:[1,0,1]
	v_pk_fma_f32 v[104:105], v[104:105], 0.5, v[226:227] op_sel_hi:[1,0,1]
	v_pk_fma_f32 v[106:107], v[106:107], 0.5, v[228:229] op_sel_hi:[1,0,1]
	s_mov_b32 s100, 0x20000
	v_lshl_add_u64 v[182:183], v[196:197], 0, s[100:101]
	global_store_dwordx4 v[182:183], v[108:111], off
	global_store_dwordx4 v[182:183], v[104:107], off offset:16
	v_cvt_pk_bf16_f32 v186, v108, v109
	v_cvt_pk_bf16_f32 v187, v110, v111
	v_cvt_pk_bf16_f32 v188, v104, v105
	v_cvt_pk_bf16_f32 v189, v106, v107
	s_mov_b32 s100, 0x10000
	v_lshl_add_u64 v[184:185], v[198:199], 0, s[100:101]
	global_store_dwordx4 v[184:185], v[186:189], off
	v_mul_f32_e32 v170, v109, v109
	v_fmac_f32_e32 v170, v108, v108
	v_fmac_f32_e32 v170, v110, v110
	v_fmac_f32_e32 v170, v111, v111
	v_fmac_f32_e32 v170, v104, v104
	v_fmac_f32_e32 v170, v105, v105
	v_fmac_f32_e32 v170, v106, v106
	v_fmac_f32_e32 v170, v107, v107
	s_mov_b32 s100, 0x60000
	v_lshl_add_u64 v[204:205], v[194:195], 0, s[100:101]
	global_load_dwordx4 v[222:225], v[204:205], off
	global_load_dwordx4 v[226:229], v[204:205], off offset:16
	s_waitcnt vmcnt(15)
; __device__ __forceinline__ unsigned pk2(float lo, float hi) { const f32v2_t v = {lo, hi}; const bf16v2_t b = __builtin_convertvector(v, bf16v2_t); return __builtin_bit_cast(unsigned, b); }
; #define ST_OUT2(p, v) __builtin_nontemporal_store((v), (p))
;     __device__ __forceinline__ void operator()(AccRef acc, const Unit& u, int wr, int wc, int fr, int fq) const {
;         const int row0 = u.pm * BM + wr * 64 + fr, col0 = u.pn * BM + wc * 32 + 8 * fq;
; #pragma unroll
;         for (int ai = 0; ai < 2; ++ai)
; #pragma unroll
;             for (int m = 0; m < 4; ++m) {
;                 const int row = row0 + ai * HALF + m * 16;
;                 float ss = 0.f;
; #pragma unroll
;                 for (int bj = 0; bj < 2; ++bj) {
;                     const size_t off = (size_t)row * DM + col0 + bj * HALF;
;                     f32x4 x0 = *(const f32x4*)(xin + off), x1 = *(const f32x4*)(xin + off + 4);
;                     x0 = x0 + acc[ai][bj][m][0] * scale; x1 = x1 + acc[ai][bj][m][1] * scale;
;                     ST_OUT2((f32x4*)(xout + off), x0); ST_OUT2((f32x4*)(xout + off + 4), x1);
;                     u32x4 o; o.x = pk2(x0[0], x0[1]); o.y = pk2(x0[2], x0[3]); o.z = pk2(x1[0], x1[1]); o.w = pk2(x1[2], x1[3]);
;                     if (wxb) ST_OUT2((u32x4*)(XB + off), o);
;                     ss += x0[0] * x0[0] + x0[1] * x0[1] + x0[2] * x0[2] + x0[3] * x0[3] + x1[0] * x1[0] + x1[1] * x1[1] + x1[2] * x1[2] + x1[3] * x1[3];
;                 }
;                 ss += __shfl_xor(ss, 16); ss += __shfl_xor(ss, 32);
;                 if (fq == 0) atomicAdd(rssn + row, (unsigned long long)(ss * 16777216.f));
	v_pk_fma_f32 v[100:101], v[100:101], 0.5, v[230:231] op_sel_hi:[1,0,1]
	v_pk_fma_f32 v[102:103], v[102:103], 0.5, v[232:233] op_sel_hi:[1,0,1]
	v_pk_fma_f32 v[96:97], v[96:97], 0.5, v[234:235] op_sel_hi:[1,0,1]
	v_pk_fma_f32 v[98:99], v[98:99], 0.5, v[236:237] op_sel_hi:[1,0,1]
	s_mov_b32 s100, 0x20000
	v_lshl_add_u64 v[182:183], v[196:197], 0, s[100:101]
	global_store_dwordx4 v[182:183], v[100:103], off offset:512
	global_store_dwordx4 v[182:183], v[96:99], off offset:528
	v_cvt_pk_bf16_f32 v186, v100, v101
	v_cvt_pk_bf16_f32 v187, v102, v103
	v_cvt_pk_bf16_f32 v188, v96, v97
	v_cvt_pk_bf16_f32 v189, v98, v99
	s_mov_b32 s100, 0x10000
	v_lshl_add_u64 v[184:185], v[198:199], 0, s[100:101]
	global_store_dwordx4 v[184:185], v[186:189], off offset:256
	v_mul_f32_e32 v171, v101, v101
	v_fmac_f32_e32 v171, v100, v100
	v_fmac_f32_e32 v171, v102, v102
	v_fmac_f32_e32 v171, v103, v103
	v_fmac_f32_e32 v171, v96, v96
	v_fmac_f32_e32 v171, v97, v97
	v_fmac_f32_e32 v171, v98, v98
	v_fmac_f32_e32 v171, v99, v99
	v_add_f32_e32 v170, v170, v171
	ds_bpermute_b32 v163, v202, v170
	s_waitcnt lgkmcnt(0)
	v_add_f32_e32 v170, v170, v163
	ds_bpermute_b32 v163, v203, v170
	s_and_saveexec_b64 s[54:55], s[38:39]
	s_waitcnt lgkmcnt(0)
	v_add_f32_e32 v170, v170, v163
	v_mul_f32_e32 v170, 0x4b800000, v170
	v_trunc_f32_e32 v170, v170
	v_mul_f32_e32 v163, 0x2f800000, v170
	v_floor_f32_e32 v163, v163
	v_fmac_f32_e32 v170, 0xcf800000, v163
	v_cvt_u32_f32_e32 v172, v170
	v_cvt_u32_f32_e32 v173, v163
	s_mov_b32 s100, 0x80
	v_lshl_add_u64 v[184:185], v[200:201], 0, s[100:101]
	global_atomic_add_x2 v[184:185], v[172:173], off
	s_or_b64 exec, exec, s[54:55]
	s_mov_b32 s100, 0x60000
	v_lshl_add_u64 v[204:205], v[194:195], 0, s[100:101]
	global_load_dwordx4 v[230:233], v[204:205], off offset:512
	global_load_dwordx4 v[234:237], v[204:205], off offset:528
	s_waitcnt vmcnt(15)
	v_pk_fma_f32 v[92:93], v[92:93], 0.5, v[206:207] op_sel_hi:[1,0,1]
	v_pk_fma_f32 v[94:95], v[94:95], 0.5, v[208:209] op_sel_hi:[1,0,1]
	v_pk_fma_f32 v[88:89], v[88:89], 0.5, v[210:211] op_sel_hi:[1,0,1]
	v_pk_fma_f32 v[90:91], v[90:91], 0.5, v[212:213] op_sel_hi:[1,0,1]
	s_mov_b32 s100, 0x40000
	v_lshl_add_u64 v[182:183], v[196:197], 0, s[100:101]
	global_store_dwordx4 v[182:183], v[92:95], off
	global_store_dwordx4 v[182:183], v[88:91], off offset:16
	v_cvt_pk_bf16_f32 v186, v92, v93
	v_cvt_pk_bf16_f32 v187, v94, v95
	v_cvt_pk_bf16_f32 v188, v88, v89
	v_cvt_pk_bf16_f32 v189, v90, v91
	s_mov_b32 s100, 0x20000
	v_lshl_add_u64 v[184:185], v[198:199], 0, s[100:101]
	global_store_dwordx4 v[184:185], v[186:189], off
	v_mul_f32_e32 v170, v93, v93
	v_fmac_f32_e32 v170, v92, v92
	v_fmac_f32_e32 v170, v94, v94
	v_fmac_f32_e32 v170, v95, v95
	v_fmac_f32_e32 v170, v88, v88
	v_fmac_f32_e32 v170, v89, v89
	v_fmac_f32_e32 v170, v90, v90
	v_fmac_f32_e32 v170, v91, v91
	s_mov_b32 s100, 0x100000
	v_lshl_add_u64 v[204:205], v[194:195], 0, s[100:101]
	global_load_dwordx4 v[206:209], v[204:205], off
	global_load_dwordx4 v[210:213], v[204:205], off offset:16
	s_waitcnt vmcnt(15)
	v_pk_fma_f32 v[84:85], v[84:85], 0.5, v[214:215] op_sel_hi:[1,0,1]
	v_pk_fma_f32 v[86:87], v[86:87], 0.5, v[216:217] op_sel_hi:[1,0,1]
	v_pk_fma_f32 v[80:81], v[80:81], 0.5, v[218:219] op_sel_hi:[1,0,1]
	v_pk_fma_f32 v[82:83], v[82:83], 0.5, v[220:221] op_sel_hi:[1,0,1]
	s_mov_b32 s100, 0x40000
	v_lshl_add_u64 v[182:183], v[196:197], 0, s[100:101]
	global_store_dwordx4 v[182:183], v[84:87], off offset:512
	global_store_dwordx4 v[182:183], v[80:83], off offset:528
	v_cvt_pk_bf16_f32 v186, v84, v85
	v_cvt_pk_bf16_f32 v187, v86, v87
	v_cvt_pk_bf16_f32 v188, v80, v81
	v_cvt_pk_bf16_f32 v189, v82, v83
	s_mov_b32 s100, 0x20000
	v_lshl_add_u64 v[184:185], v[198:199], 0, s[100:101]
	global_store_dwordx4 v[184:185], v[186:189], off offset:256
	v_mul_f32_e32 v171, v85, v85
	v_fmac_f32_e32 v171, v84, v84
	v_fmac_f32_e32 v171, v86, v86
	v_fmac_f32_e32 v171, v87, v87
	v_fmac_f32_e32 v171, v80, v80
	v_fmac_f32_e32 v171, v81, v81
	v_fmac_f32_e32 v171, v82, v82
	v_fmac_f32_e32 v171, v83, v83
	v_add_f32_e32 v170, v170, v171
	ds_bpermute_b32 v163, v202, v170
	s_waitcnt lgkmcnt(0)
	v_add_f32_e32 v170, v170, v163
	ds_bpermute_b32 v163, v203, v170
	s_and_saveexec_b64 s[54:55], s[38:39]
	s_waitcnt lgkmcnt(0)
	v_add_f32_e32 v170, v170, v163
	v_mul_f32_e32 v170, 0x4b800000, v170
	v_trunc_f32_e32 v170, v170
	v_mul_f32_e32 v163, 0x2f800000, v170
	v_floor_f32_e32 v163, v163
	v_fmac_f32_e32 v170, 0xcf800000, v163
	v_cvt_u32_f32_e32 v172, v170
	v_cvt_u32_f32_e32 v173, v163
	s_mov_b32 s100, 0x100
	v_lshl_add_u64 v[184:185], v[200:201], 0, s[100:101]
	global_atomic_add_x2 v[184:185], v[172:173], off
	s_or_b64 exec, exec, s[54:55]
	s_mov_b32 s100, 0x100000
	v_lshl_add_u64 v[204:205], v[194:195], 0, s[100:101]
	global_load_dwordx4 v[214:217], v[204:205], off offset:512
	global_load_dwordx4 v[218:221], v[204:205], off offset:528
	s_waitcnt vmcnt(15)
	v_pk_fma_f32 v[76:77], v[76:77], 0.5, v[222:223] op_sel_hi:[1,0,1]
	v_pk_fma_f32 v[78:79], v[78:79], 0.5, v[224:225] op_sel_hi:[1,0,1]
	v_pk_fma_f32 v[72:73], v[72:73], 0.5, v[226:227] op_sel_hi:[1,0,1]
	v_pk_fma_f32 v[74:75], v[74:75], 0.5, v[228:229] op_sel_hi:[1,0,1]
	s_mov_b32 s100, 0x60000
	v_lshl_add_u64 v[182:183], v[196:197], 0, s[100:101]
	global_store_dwordx4 v[182:183], v[76:79], off
	global_store_dwordx4 v[182:183], v[72:75], off offset:16
	v_cvt_pk_bf16_f32 v186, v76, v77
	v_cvt_pk_bf16_f32 v187, v78, v79
	v_cvt_pk_bf16_f32 v188, v72, v73
	v_cvt_pk_bf16_f32 v189, v74, v75
	s_mov_b32 s100, 0x30000
	v_lshl_add_u64 v[184:185], v[198:199], 0, s[100:101]
	global_store_dwordx4 v[184:185], v[186:189], off
	v_mul_f32_e32 v170, v77, v77
	v_fmac_f32_e32 v170, v76, v76
	v_fmac_f32_e32 v170, v78, v78
	v_fmac_f32_e32 v170, v79, v79
	v_fmac_f32_e32 v170, v72, v72
	v_fmac_f32_e32 v170, v73, v73
	v_fmac_f32_e32 v170, v74, v74
	v_fmac_f32_e32 v170, v75, v75
	s_mov_b32 s100, 0x120000
	v_lshl_add_u64 v[204:205], v[194:195], 0, s[100:101]
	global_load_dwordx4 v[222:225], v[204:205], off
	global_load_dwordx4 v[226:229], v[204:205], off offset:16
	s_waitcnt vmcnt(15)
; __device__ __forceinline__ unsigned pk2(float lo, float hi) { const f32v2_t v = {lo, hi}; const bf16v2_t b = __builtin_convertvector(v, bf16v2_t); return __builtin_bit_cast(unsigned, b); }
; #define ST_OUT2(p, v) __builtin_nontemporal_store((v), (p))
;     __device__ __forceinline__ void operator()(AccRef acc, const Unit& u, int wr, int wc, int fr, int fq) const {
;         const int row0 = u.pm * BM + wr * 64 + fr, col0 = u.pn * BM + wc * 32 + 8 * fq;
; #pragma unroll
;         for (int ai = 0; ai < 2; ++ai)
; #pragma unroll
;             for (int m = 0; m < 4; ++m) {
;                 const int row = row0 + ai * HALF + m * 16;
;                 float ss = 0.f;
; #pragma unroll
;                 for (int bj = 0; bj < 2; ++bj) {
;                     const size_t off = (size_t)row * DM + col0 + bj * HALF;
;                     f32x4 x0 = *(const f32x4*)(xin + off), x1 = *(const f32x4*)(xin + off + 4);
;                     x0 = x0 + acc[ai][bj][m][0] * scale; x1 = x1 + acc[ai][bj][m][1] * scale;
;                     ST_OUT2((f32x4*)(xout + off), x0); ST_OUT2((f32x4*)(xout + off + 4), x1);
;                     u32x4 o; o.x = pk2(x0[0], x0[1]); o.y = pk2(x0[2], x0[3]); o.z = pk2(x1[0], x1[1]); o.w = pk2(x1[2], x1[3]);
;                     if (wxb) ST_OUT2((u32x4*)(XB + off), o);
;                     ss += x0[0] * x0[0] + x0[1] * x0[1] + x0[2] * x0[2] + x0[3] * x0[3] + x1[0] * x1[0] + x1[1] * x1[1] + x1[2] * x1[2] + x1[3] * x1[3];
;                 }
;                 ss += __shfl_xor(ss, 16); ss += __shfl_xor(ss, 32);
;                 if (fq == 0) atomicAdd(rssn + row, (unsigned long long)(ss * 16777216.f));
	v_pk_fma_f32 v[68:69], v[68:69], 0.5, v[230:231] op_sel_hi:[1,0,1]
	v_pk_fma_f32 v[70:71], v[70:71], 0.5, v[232:233] op_sel_hi:[1,0,1]
	v_pk_fma_f32 v[64:65], v[64:65], 0.5, v[234:235] op_sel_hi:[1,0,1]
	v_pk_fma_f32 v[66:67], v[66:67], 0.5, v[236:237] op_sel_hi:[1,0,1]
	s_mov_b32 s100, 0x60000
	v_lshl_add_u64 v[182:183], v[196:197], 0, s[100:101]
	global_store_dwordx4 v[182:183], v[68:71], off offset:512
	global_store_dwordx4 v[182:183], v[64:67], off offset:528
	v_cvt_pk_bf16_f32 v186, v68, v69
	v_cvt_pk_bf16_f32 v187, v70, v71
	v_cvt_pk_bf16_f32 v188, v64, v65
	v_cvt_pk_bf16_f32 v189, v66, v67
	s_mov_b32 s100, 0x30000
	v_lshl_add_u64 v[184:185], v[198:199], 0, s[100:101]
	global_store_dwordx4 v[184:185], v[186:189], off offset:256
	v_mul_f32_e32 v171, v69, v69
	v_fmac_f32_e32 v171, v68, v68
	v_fmac_f32_e32 v171, v70, v70
	v_fmac_f32_e32 v171, v71, v71
	v_fmac_f32_e32 v171, v64, v64
	v_fmac_f32_e32 v171, v65, v65
	v_fmac_f32_e32 v171, v66, v66
	v_fmac_f32_e32 v171, v67, v67
	v_add_f32_e32 v170, v170, v171
	ds_bpermute_b32 v163, v202, v170
	s_waitcnt lgkmcnt(0)
	v_add_f32_e32 v170, v170, v163
	ds_bpermute_b32 v163, v203, v170
	s_and_saveexec_b64 s[54:55], s[38:39]
	s_waitcnt lgkmcnt(0)
	v_add_f32_e32 v170, v170, v163
	v_mul_f32_e32 v170, 0x4b800000, v170
	v_trunc_f32_e32 v170, v170
	v_mul_f32_e32 v163, 0x2f800000, v170
	v_floor_f32_e32 v163, v163
	v_fmac_f32_e32 v170, 0xcf800000, v163
	v_cvt_u32_f32_e32 v172, v170
	v_cvt_u32_f32_e32 v173, v163
	s_mov_b32 s100, 0x180
	v_lshl_add_u64 v[184:185], v[200:201], 0, s[100:101]
	global_atomic_add_x2 v[184:185], v[172:173], off
	s_or_b64 exec, exec, s[54:55]
	s_mov_b32 s100, 0x120000
	v_lshl_add_u64 v[204:205], v[194:195], 0, s[100:101]
	global_load_dwordx4 v[230:233], v[204:205], off offset:512
	global_load_dwordx4 v[234:237], v[204:205], off offset:528
	s_waitcnt vmcnt(15)
	v_pk_fma_f32 v[60:61], v[60:61], 0.5, v[206:207] op_sel_hi:[1,0,1]
	v_pk_fma_f32 v[62:63], v[62:63], 0.5, v[208:209] op_sel_hi:[1,0,1]
	v_pk_fma_f32 v[56:57], v[56:57], 0.5, v[210:211] op_sel_hi:[1,0,1]
	v_pk_fma_f32 v[58:59], v[58:59], 0.5, v[212:213] op_sel_hi:[1,0,1]
	s_mov_b32 s100, 0x100000
	v_lshl_add_u64 v[182:183], v[196:197], 0, s[100:101]
	global_store_dwordx4 v[182:183], v[60:63], off
	global_store_dwordx4 v[182:183], v[56:59], off offset:16
	v_cvt_pk_bf16_f32 v186, v60, v61
	v_cvt_pk_bf16_f32 v187, v62, v63
	v_cvt_pk_bf16_f32 v188, v56, v57
	v_cvt_pk_bf16_f32 v189, v58, v59
	s_mov_b32 s100, 0x80000
	v_lshl_add_u64 v[184:185], v[198:199], 0, s[100:101]
	global_store_dwordx4 v[184:185], v[186:189], off
	v_mul_f32_e32 v170, v61, v61
	v_fmac_f32_e32 v170, v60, v60
	v_fmac_f32_e32 v170, v62, v62
	v_fmac_f32_e32 v170, v63, v63
	v_fmac_f32_e32 v170, v56, v56
	v_fmac_f32_e32 v170, v57, v57
	v_fmac_f32_e32 v170, v58, v58
	v_fmac_f32_e32 v170, v59, v59
	s_mov_b32 s100, 0x140000
	v_lshl_add_u64 v[204:205], v[194:195], 0, s[100:101]
	global_load_dwordx4 v[206:209], v[204:205], off
	global_load_dwordx4 v[210:213], v[204:205], off offset:16
	s_waitcnt vmcnt(15)
	v_pk_fma_f32 v[52:53], v[52:53], 0.5, v[214:215] op_sel_hi:[1,0,1]
	v_pk_fma_f32 v[54:55], v[54:55], 0.5, v[216:217] op_sel_hi:[1,0,1]
	v_pk_fma_f32 v[48:49], v[48:49], 0.5, v[218:219] op_sel_hi:[1,0,1]
	v_pk_fma_f32 v[50:51], v[50:51], 0.5, v[220:221] op_sel_hi:[1,0,1]
	s_mov_b32 s100, 0x100000
	v_lshl_add_u64 v[182:183], v[196:197], 0, s[100:101]
	global_store_dwordx4 v[182:183], v[52:55], off offset:512
	global_store_dwordx4 v[182:183], v[48:51], off offset:528
	v_cvt_pk_bf16_f32 v186, v52, v53
	v_cvt_pk_bf16_f32 v187, v54, v55
	v_cvt_pk_bf16_f32 v188, v48, v49
	v_cvt_pk_bf16_f32 v189, v50, v51
	s_mov_b32 s100, 0x80000
	v_lshl_add_u64 v[184:185], v[198:199], 0, s[100:101]
	global_store_dwordx4 v[184:185], v[186:189], off offset:256
	v_mul_f32_e32 v171, v53, v53
	v_fmac_f32_e32 v171, v52, v52
	v_fmac_f32_e32 v171, v54, v54
	v_fmac_f32_e32 v171, v55, v55
	v_fmac_f32_e32 v171, v48, v48
	v_fmac_f32_e32 v171, v49, v49
	v_fmac_f32_e32 v171, v50, v50
	v_fmac_f32_e32 v171, v51, v51
	v_add_f32_e32 v170, v170, v171
	ds_bpermute_b32 v163, v202, v170
	s_waitcnt lgkmcnt(0)
	v_add_f32_e32 v170, v170, v163
	ds_bpermute_b32 v163, v203, v170
	s_and_saveexec_b64 s[54:55], s[38:39]
	s_waitcnt lgkmcnt(0)
	v_add_f32_e32 v170, v170, v163
	v_mul_f32_e32 v170, 0x4b800000, v170
	v_trunc_f32_e32 v170, v170
	v_mul_f32_e32 v163, 0x2f800000, v170
	v_floor_f32_e32 v163, v163
	v_fmac_f32_e32 v170, 0xcf800000, v163
	v_cvt_u32_f32_e32 v172, v170
	v_cvt_u32_f32_e32 v173, v163
	s_mov_b32 s100, 0x400
	v_lshl_add_u64 v[184:185], v[200:201], 0, s[100:101]
	global_atomic_add_x2 v[184:185], v[172:173], off
	s_or_b64 exec, exec, s[54:55]
	s_mov_b32 s100, 0x140000
	v_lshl_add_u64 v[204:205], v[194:195], 0, s[100:101]
	global_load_dwordx4 v[214:217], v[204:205], off offset:512
	global_load_dwordx4 v[218:221], v[204:205], off offset:528
	s_waitcnt vmcnt(15)
	v_pk_fma_f32 v[44:45], v[44:45], 0.5, v[222:223] op_sel_hi:[1,0,1]
	v_pk_fma_f32 v[46:47], v[46:47], 0.5, v[224:225] op_sel_hi:[1,0,1]
	v_pk_fma_f32 v[40:41], v[40:41], 0.5, v[226:227] op_sel_hi:[1,0,1]
	v_pk_fma_f32 v[42:43], v[42:43], 0.5, v[228:229] op_sel_hi:[1,0,1]
	s_mov_b32 s100, 0x120000
	v_lshl_add_u64 v[182:183], v[196:197], 0, s[100:101]
	global_store_dwordx4 v[182:183], v[44:47], off
	global_store_dwordx4 v[182:183], v[40:43], off offset:16
	v_cvt_pk_bf16_f32 v186, v44, v45
	v_cvt_pk_bf16_f32 v187, v46, v47
	v_cvt_pk_bf16_f32 v188, v40, v41
	v_cvt_pk_bf16_f32 v189, v42, v43
	s_mov_b32 s100, 0x90000
	v_lshl_add_u64 v[184:185], v[198:199], 0, s[100:101]
	global_store_dwordx4 v[184:185], v[186:189], off
	v_mul_f32_e32 v170, v45, v45
	v_fmac_f32_e32 v170, v44, v44
	v_fmac_f32_e32 v170, v46, v46
	v_fmac_f32_e32 v170, v47, v47
	v_fmac_f32_e32 v170, v40, v40
	v_fmac_f32_e32 v170, v41, v41
	v_fmac_f32_e32 v170, v42, v42
	v_fmac_f32_e32 v170, v43, v43
	s_mov_b32 s100, 0x160000
	v_lshl_add_u64 v[204:205], v[194:195], 0, s[100:101]
	global_load_dwordx4 v[222:225], v[204:205], off
	global_load_dwordx4 v[226:229], v[204:205], off offset:16
	s_waitcnt vmcnt(15)
; __device__ __forceinline__ unsigned pk2(float lo, float hi) { const f32v2_t v = {lo, hi}; const bf16v2_t b = __builtin_convertvector(v, bf16v2_t); return __builtin_bit_cast(unsigned, b); }
; #define ST_OUT2(p, v) __builtin_nontemporal_store((v), (p))
;     __device__ __forceinline__ void operator()(AccRef acc, const Unit& u, int wr, int wc, int fr, int fq) const {
;         const int row0 = u.pm * BM + wr * 64 + fr, col0 = u.pn * BM + wc * 32 + 8 * fq;
; #pragma unroll
;         for (int ai = 0; ai < 2; ++ai)
; #pragma unroll
;             for (int m = 0; m < 4; ++m) {
;                 const int row = row0 + ai * HALF + m * 16;
;                 float ss = 0.f;
; #pragma unroll
;                 for (int bj = 0; bj < 2; ++bj) {
;                     const size_t off = (size_t)row * DM + col0 + bj * HALF;
;                     f32x4 x0 = *(const f32x4*)(xin + off), x1 = *(const f32x4*)(xin + off + 4);
;                     x0 = x0 + acc[ai][bj][m][0] * scale; x1 = x1 + acc[ai][bj][m][1] * scale;
;                     ST_OUT2((f32x4*)(xout + off), x0); ST_OUT2((f32x4*)(xout + off + 4), x1);
;                     u32x4 o; o.x = pk2(x0[0], x0[1]); o.y = pk2(x0[2], x0[3]); o.z = pk2(x1[0], x1[1]); o.w = pk2(x1[2], x1[3]);
;                     if (wxb) ST_OUT2((u32x4*)(XB + off), o);
;                     ss += x0[0] * x0[0] + x0[1] * x0[1] + x0[2] * x0[2] + x0[3] * x0[3] + x1[0] * x1[0] + x1[1] * x1[1] + x1[2] * x1[2] + x1[3] * x1[3];
;                 }
;                 ss += __shfl_xor(ss, 16); ss += __shfl_xor(ss, 32);
;                 if (fq == 0) atomicAdd(rssn + row, (unsigned long long)(ss * 16777216.f));
	v_pk_fma_f32 v[36:37], v[36:37], 0.5, v[230:231] op_sel_hi:[1,0,1]
	v_pk_fma_f32 v[38:39], v[38:39], 0.5, v[232:233] op_sel_hi:[1,0,1]
	v_pk_fma_f32 v[32:33], v[32:33], 0.5, v[234:235] op_sel_hi:[1,0,1]
	v_pk_fma_f32 v[34:35], v[34:35], 0.5, v[236:237] op_sel_hi:[1,0,1]
	s_mov_b32 s100, 0x120000
	v_lshl_add_u64 v[182:183], v[196:197], 0, s[100:101]
	global_store_dwordx4 v[182:183], v[36:39], off offset:512
	global_store_dwordx4 v[182:183], v[32:35], off offset:528
	v_cvt_pk_bf16_f32 v186, v36, v37
	v_cvt_pk_bf16_f32 v187, v38, v39
	v_cvt_pk_bf16_f32 v188, v32, v33
	v_cvt_pk_bf16_f32 v189, v34, v35
	s_mov_b32 s100, 0x90000
	v_lshl_add_u64 v[184:185], v[198:199], 0, s[100:101]
	global_store_dwordx4 v[184:185], v[186:189], off offset:256
	v_mul_f32_e32 v171, v37, v37
	v_fmac_f32_e32 v171, v36, v36
	v_fmac_f32_e32 v171, v38, v38
	v_fmac_f32_e32 v171, v39, v39
	v_fmac_f32_e32 v171, v32, v32
	v_fmac_f32_e32 v171, v33, v33
	v_fmac_f32_e32 v171, v34, v34
	v_fmac_f32_e32 v171, v35, v35
	v_add_f32_e32 v170, v170, v171
	ds_bpermute_b32 v163, v202, v170
	s_waitcnt lgkmcnt(0)
	v_add_f32_e32 v170, v170, v163
	ds_bpermute_b32 v163, v203, v170
	s_and_saveexec_b64 s[54:55], s[38:39]
	s_waitcnt lgkmcnt(0)
	v_add_f32_e32 v170, v170, v163
	v_mul_f32_e32 v170, 0x4b800000, v170
	v_trunc_f32_e32 v170, v170
	v_mul_f32_e32 v163, 0x2f800000, v170
	v_floor_f32_e32 v163, v163
	v_fmac_f32_e32 v170, 0xcf800000, v163
	v_cvt_u32_f32_e32 v172, v170
	v_cvt_u32_f32_e32 v173, v163
	s_mov_b32 s100, 0x480
	v_lshl_add_u64 v[184:185], v[200:201], 0, s[100:101]
	global_atomic_add_x2 v[184:185], v[172:173], off
	s_or_b64 exec, exec, s[54:55]
	s_mov_b32 s100, 0x160000
	v_lshl_add_u64 v[204:205], v[194:195], 0, s[100:101]
	global_load_dwordx4 v[230:233], v[204:205], off offset:512
	global_load_dwordx4 v[234:237], v[204:205], off offset:528
	s_waitcnt vmcnt(15)
	v_pk_fma_f32 v[28:29], v[28:29], 0.5, v[206:207] op_sel_hi:[1,0,1]
	v_pk_fma_f32 v[30:31], v[30:31], 0.5, v[208:209] op_sel_hi:[1,0,1]
	v_pk_fma_f32 v[24:25], v[24:25], 0.5, v[210:211] op_sel_hi:[1,0,1]
	v_pk_fma_f32 v[26:27], v[26:27], 0.5, v[212:213] op_sel_hi:[1,0,1]
	s_mov_b32 s100, 0x140000
	v_lshl_add_u64 v[182:183], v[196:197], 0, s[100:101]
	global_store_dwordx4 v[182:183], v[28:31], off
	global_store_dwordx4 v[182:183], v[24:27], off offset:16
	v_cvt_pk_bf16_f32 v186, v28, v29
	v_cvt_pk_bf16_f32 v187, v30, v31
	v_cvt_pk_bf16_f32 v188, v24, v25
	v_cvt_pk_bf16_f32 v189, v26, v27
	s_mov_b32 s100, 0xa0000
	v_lshl_add_u64 v[184:185], v[198:199], 0, s[100:101]
	global_store_dwordx4 v[184:185], v[186:189], off
	v_mul_f32_e32 v170, v29, v29
	v_fmac_f32_e32 v170, v28, v28
	v_fmac_f32_e32 v170, v30, v30
	v_fmac_f32_e32 v170, v31, v31
	v_fmac_f32_e32 v170, v24, v24
	v_fmac_f32_e32 v170, v25, v25
	v_fmac_f32_e32 v170, v26, v26
	v_fmac_f32_e32 v170, v27, v27
	s_waitcnt vmcnt(13)
	v_pk_fma_f32 v[20:21], v[20:21], 0.5, v[214:215] op_sel_hi:[1,0,1]
	v_pk_fma_f32 v[22:23], v[22:23], 0.5, v[216:217] op_sel_hi:[1,0,1]
	v_pk_fma_f32 v[16:17], v[16:17], 0.5, v[218:219] op_sel_hi:[1,0,1]
	v_pk_fma_f32 v[18:19], v[18:19], 0.5, v[220:221] op_sel_hi:[1,0,1]
	s_mov_b32 s100, 0x140000
	v_lshl_add_u64 v[182:183], v[196:197], 0, s[100:101]
	global_store_dwordx4 v[182:183], v[20:23], off offset:512
	global_store_dwordx4 v[182:183], v[16:19], off offset:528
	v_cvt_pk_bf16_f32 v186, v20, v21
	v_cvt_pk_bf16_f32 v187, v22, v23
	v_cvt_pk_bf16_f32 v188, v16, v17
	v_cvt_pk_bf16_f32 v189, v18, v19
	s_mov_b32 s100, 0xa0000
	v_lshl_add_u64 v[184:185], v[198:199], 0, s[100:101]
	global_store_dwordx4 v[184:185], v[186:189], off offset:256
	v_mul_f32_e32 v171, v21, v21
	v_fmac_f32_e32 v171, v20, v20
	v_fmac_f32_e32 v171, v22, v22
	v_fmac_f32_e32 v171, v23, v23
	v_fmac_f32_e32 v171, v16, v16
	v_fmac_f32_e32 v171, v17, v17
	v_fmac_f32_e32 v171, v18, v18
	v_fmac_f32_e32 v171, v19, v19
	v_add_f32_e32 v170, v170, v171
	ds_bpermute_b32 v163, v202, v170
	s_waitcnt lgkmcnt(0)
	v_add_f32_e32 v170, v170, v163
	ds_bpermute_b32 v163, v203, v170
	s_and_saveexec_b64 s[54:55], s[38:39]
	s_waitcnt lgkmcnt(0)
	v_add_f32_e32 v170, v170, v163
	v_mul_f32_e32 v170, 0x4b800000, v170
	v_trunc_f32_e32 v170, v170
	v_mul_f32_e32 v163, 0x2f800000, v170
	v_floor_f32_e32 v163, v163
	v_fmac_f32_e32 v170, 0xcf800000, v163
	v_cvt_u32_f32_e32 v172, v170
	v_cvt_u32_f32_e32 v173, v163
	s_mov_b32 s100, 0x500
	v_lshl_add_u64 v[184:185], v[200:201], 0, s[100:101]
	global_atomic_add_x2 v[184:185], v[172:173], off
	s_or_b64 exec, exec, s[54:55]
	s_waitcnt vmcnt(11)
	v_pk_fma_f32 v[12:13], v[12:13], 0.5, v[222:223] op_sel_hi:[1,0,1]
	v_pk_fma_f32 v[14:15], v[14:15], 0.5, v[224:225] op_sel_hi:[1,0,1]
	v_pk_fma_f32 v[8:9], v[8:9], 0.5, v[226:227] op_sel_hi:[1,0,1]
	v_pk_fma_f32 v[10:11], v[10:11], 0.5, v[228:229] op_sel_hi:[1,0,1]
	s_mov_b32 s100, 0x160000
	v_lshl_add_u64 v[182:183], v[196:197], 0, s[100:101]
	global_store_dwordx4 v[182:183], v[12:15], off
	global_store_dwordx4 v[182:183], v[8:11], off offset:16
	v_cvt_pk_bf16_f32 v186, v12, v13
	v_cvt_pk_bf16_f32 v187, v14, v15
	v_cvt_pk_bf16_f32 v188, v8, v9
	v_cvt_pk_bf16_f32 v189, v10, v11
	s_mov_b32 s100, 0xb0000
	v_lshl_add_u64 v[184:185], v[198:199], 0, s[100:101]
	global_store_dwordx4 v[184:185], v[186:189], off
	v_mul_f32_e32 v170, v13, v13
	v_fmac_f32_e32 v170, v12, v12
	v_fmac_f32_e32 v170, v14, v14
	v_fmac_f32_e32 v170, v15, v15
	v_fmac_f32_e32 v170, v8, v8
	v_fmac_f32_e32 v170, v9, v9
	v_fmac_f32_e32 v170, v10, v10
	v_fmac_f32_e32 v170, v11, v11
	s_waitcnt vmcnt(9)
; __device__ __forceinline__ unsigned pk2(float lo, float hi) { const f32v2_t v = {lo, hi}; const bf16v2_t b = __builtin_convertvector(v, bf16v2_t); return __builtin_bit_cast(unsigned, b); }
; #define ST_OUT2(p, v) __builtin_nontemporal_store((v), (p))
;     __device__ __forceinline__ void operator()(AccRef acc, const Unit& u, int wr, int wc, int fr, int fq) const {
;         const int row0 = u.pm * BM + wr * 64 + fr, col0 = u.pn * BM + wc * 32 + 8 * fq;
; #pragma unroll
;         for (int ai = 0; ai < 2; ++ai)
; #pragma unroll
;             for (int m = 0; m < 4; ++m) {
;                 const int row = row0 + ai * HALF + m * 16;
;                 float ss = 0.f;
; #pragma unroll
;                 for (int bj = 0; bj < 2; ++bj) {
;                     const size_t off = (size_t)row * DM + col0 + bj * HALF;
;                     f32x4 x0 = *(const f32x4*)(xin + off), x1 = *(const f32x4*)(xin + off + 4);
;                     x0 = x0 + acc[ai][bj][m][0] * scale; x1 = x1 + acc[ai][bj][m][1] * scale;
;                     ST_OUT2((f32x4*)(xout + off), x0); ST_OUT2((f32x4*)(xout + off + 4), x1);
;                     u32x4 o; o.x = pk2(x0[0], x0[1]); o.y = pk2(x0[2], x0[3]); o.z = pk2(x1[0], x1[1]); o.w = pk2(x1[2], x1[3]);
;                     if (wxb) ST_OUT2((u32x4*)(XB + off), o);
;                     ss += x0[0] * x0[0] + x0[1] * x0[1] + x0[2] * x0[2] + x0[3] * x0[3] + x1[0] * x1[0] + x1[1] * x1[1] + x1[2] * x1[2] + x1[3] * x1[3];
;                 }
;                 ss += __shfl_xor(ss, 16); ss += __shfl_xor(ss, 32);
;                 if (fq == 0) atomicAdd(rssn + row, (unsigned long long)(ss * 16777216.f));
;             }
;     }
	v_pk_fma_f32 v[4:5], v[4:5], 0.5, v[230:231] op_sel_hi:[1,0,1]
	v_pk_fma_f32 v[6:7], v[6:7], 0.5, v[232:233] op_sel_hi:[1,0,1]
	v_pk_fma_f32 v[0:1], v[0:1], 0.5, v[234:235] op_sel_hi:[1,0,1]
	v_pk_fma_f32 v[2:3], v[2:3], 0.5, v[236:237] op_sel_hi:[1,0,1]
	s_mov_b32 s100, 0x160000
	v_lshl_add_u64 v[182:183], v[196:197], 0, s[100:101]
	global_store_dwordx4 v[182:183], v[4:7], off offset:512
	global_store_dwordx4 v[182:183], v[0:3], off offset:528
	v_cvt_pk_bf16_f32 v186, v4, v5
	v_cvt_pk_bf16_f32 v187, v6, v7
	v_cvt_pk_bf16_f32 v188, v0, v1
	v_cvt_pk_bf16_f32 v189, v2, v3
	s_mov_b32 s100, 0xb0000
	v_lshl_add_u64 v[184:185], v[198:199], 0, s[100:101]
	global_store_dwordx4 v[184:185], v[186:189], off offset:256
	v_mul_f32_e32 v171, v5, v5
	v_fmac_f32_e32 v171, v4, v4
	v_fmac_f32_e32 v171, v6, v6
	v_fmac_f32_e32 v171, v7, v7
	v_fmac_f32_e32 v171, v0, v0
	v_fmac_f32_e32 v171, v1, v1
	v_fmac_f32_e32 v171, v2, v2
	v_fmac_f32_e32 v171, v3, v3
	v_add_f32_e32 v170, v170, v171
	ds_bpermute_b32 v163, v202, v170
	s_waitcnt lgkmcnt(0)
	v_add_f32_e32 v170, v170, v163
	ds_bpermute_b32 v163, v203, v170
	s_and_saveexec_b64 s[54:55], s[38:39]
	s_waitcnt lgkmcnt(0)
	v_add_f32_e32 v170, v170, v163
	v_mul_f32_e32 v170, 0x4b800000, v170
	v_trunc_f32_e32 v170, v170
	v_mul_f32_e32 v163, 0x2f800000, v170
	v_floor_f32_e32 v163, v163
	v_fmac_f32_e32 v170, 0xcf800000, v163
	v_cvt_u32_f32_e32 v172, v170
	v_cvt_u32_f32_e32 v173, v163
	s_mov_b32 s100, 0x580
	v_lshl_add_u64 v[184:185], v[200:201], 0, s[100:101]
	global_atomic_add_x2 v[184:185], v[172:173], off
	s_or_b64 exec, exec, s[54:55]
	s_branch .Lrs2_done
.Lrs2_nowxb:
	s_mov_b32 s100, 0x0
	v_lshl_add_u64 v[204:205], v[194:195], 0, s[100:101]
	global_load_dwordx4 v[206:209], v[204:205], off
	global_load_dwordx4 v[210:213], v[204:205], off offset:16
	s_mov_b32 s100, 0x0
	v_lshl_add_u64 v[204:205], v[194:195], 0, s[100:101]
	global_load_dwordx4 v[214:217], v[204:205], off offset:512
	global_load_dwordx4 v[218:221], v[204:205], off offset:528
	s_mov_b32 s100, 0x20000
	v_lshl_add_u64 v[204:205], v[194:195], 0, s[100:101]
	global_load_dwordx4 v[222:225], v[204:205], off
	global_load_dwordx4 v[226:229], v[204:205], off offset:16
	s_mov_b32 s100, 0x20000
	v_lshl_add_u64 v[204:205], v[194:195], 0, s[100:101]
	global_load_dwordx4 v[230:233], v[204:205], off offset:512
	global_load_dwordx4 v[234:237], v[204:205], off offset:528
	s_waitcnt vmcnt(6)
	v_pk_fma_f32 v[124:125], v[124:125], 0.5, v[206:207] op_sel_hi:[1,0,1]
	v_pk_fma_f32 v[126:127], v[126:127], 0.5, v[208:209] op_sel_hi:[1,0,1]
	v_pk_fma_f32 v[120:121], v[120:121], 0.5, v[210:211] op_sel_hi:[1,0,1]
	v_pk_fma_f32 v[122:123], v[122:123], 0.5, v[212:213] op_sel_hi:[1,0,1]
	s_mov_b32 s100, 0x0
	v_lshl_add_u64 v[182:183], v[196:197], 0, s[100:101]
	global_store_dwordx4 v[182:183], v[124:127], off
	global_store_dwordx4 v[182:183], v[120:123], off offset:16
	v_mul_f32_e32 v170, v125, v125
	v_fmac_f32_e32 v170, v124, v124
	v_fmac_f32_e32 v170, v126, v126
	v_fmac_f32_e32 v170, v127, v127
	v_fmac_f32_e32 v170, v120, v120
	v_fmac_f32_e32 v170, v121, v121
	v_fmac_f32_e32 v170, v122, v122
	v_fmac_f32_e32 v170, v123, v123
	s_mov_b32 s100, 0x40000
	v_lshl_add_u64 v[204:205], v[194:195], 0, s[100:101]
	global_load_dwordx4 v[206:209], v[204:205], off
	global_load_dwordx4 v[210:213], v[204:205], off offset:16
	s_waitcnt vmcnt(8)
	v_pk_fma_f32 v[116:117], v[116:117], 0.5, v[214:215] op_sel_hi:[1,0,1]
	v_pk_fma_f32 v[118:119], v[118:119], 0.5, v[216:217] op_sel_hi:[1,0,1]
	v_pk_fma_f32 v[112:113], v[112:113], 0.5, v[218:219] op_sel_hi:[1,0,1]
	v_pk_fma_f32 v[114:115], v[114:115], 0.5, v[220:221] op_sel_hi:[1,0,1]
	s_mov_b32 s100, 0x0
	v_lshl_add_u64 v[182:183], v[196:197], 0, s[100:101]
	global_store_dwordx4 v[182:183], v[116:119], off offset:512
	global_store_dwordx4 v[182:183], v[112:115], off offset:528
	v_mul_f32_e32 v171, v117, v117
	v_fmac_f32_e32 v171, v116, v116
	v_fmac_f32_e32 v171, v118, v118
	v_fmac_f32_e32 v171, v119, v119
	v_fmac_f32_e32 v171, v112, v112
	v_fmac_f32_e32 v171, v113, v113
	v_fmac_f32_e32 v171, v114, v114
	v_fmac_f32_e32 v171, v115, v115
	v_add_f32_e32 v170, v170, v171
	ds_bpermute_b32 v163, v202, v170
	s_waitcnt lgkmcnt(0)
	v_add_f32_e32 v170, v170, v163
	ds_bpermute_b32 v163, v203, v170
	s_and_saveexec_b64 s[54:55], s[38:39]
	s_waitcnt lgkmcnt(0)
	v_add_f32_e32 v170, v170, v163
	v_mul_f32_e32 v170, 0x4b800000, v170
	v_trunc_f32_e32 v170, v170
	v_mul_f32_e32 v163, 0x2f800000, v170
	v_floor_f32_e32 v163, v163
	v_fmac_f32_e32 v170, 0xcf800000, v163
	v_cvt_u32_f32_e32 v172, v170
	v_cvt_u32_f32_e32 v173, v163
	s_mov_b32 s100, 0x0
	v_lshl_add_u64 v[184:185], v[200:201], 0, s[100:101]
	global_atomic_add_x2 v[184:185], v[172:173], off
	s_or_b64 exec, exec, s[54:55]
	s_mov_b32 s100, 0x40000
	v_lshl_add_u64 v[204:205], v[194:195], 0, s[100:101]
	global_load_dwordx4 v[214:217], v[204:205], off offset:512
	global_load_dwordx4 v[218:221], v[204:205], off offset:528
	s_waitcnt vmcnt(10)
	v_pk_fma_f32 v[108:109], v[108:109], 0.5, v[222:223] op_sel_hi:[1,0,1]
	v_pk_fma_f32 v[110:111], v[110:111], 0.5, v[224:225] op_sel_hi:[1,0,1]
	v_pk_fma_f32 v[104:105], v[104:105], 0.5, v[226:227] op_sel_hi:[1,0,1]
	v_pk_fma_f32 v[106:107], v[106:107], 0.5, v[228:229] op_sel_hi:[1,0,1]
	s_mov_b32 s100, 0x20000
	v_lshl_add_u64 v[182:183], v[196:197], 0, s[100:101]
	global_store_dwordx4 v[182:183], v[108:111], off
	global_store_dwordx4 v[182:183], v[104:107], off offset:16
	v_mul_f32_e32 v170, v109, v109
	v_fmac_f32_e32 v170, v108, v108
	v_fmac_f32_e32 v170, v110, v110
	v_fmac_f32_e32 v170, v111, v111
	v_fmac_f32_e32 v170, v104, v104
	v_fmac_f32_e32 v170, v105, v105
	v_fmac_f32_e32 v170, v106, v106
	v_fmac_f32_e32 v170, v107, v107
	s_mov_b32 s100, 0x60000
	v_lshl_add_u64 v[204:205], v[194:195], 0, s[100:101]
	global_load_dwordx4 v[222:225], v[204:205], off
	global_load_dwordx4 v[226:229], v[204:205], off offset:16
	s_waitcnt vmcnt(12)
; __device__ __forceinline__ unsigned pk2(float lo, float hi) { const f32v2_t v = {lo, hi}; const bf16v2_t b = __builtin_convertvector(v, bf16v2_t); return __builtin_bit_cast(unsigned, b); }
; #define ST_OUT2(p, v) __builtin_nontemporal_store((v), (p))
;     __device__ __forceinline__ void operator()(AccRef acc, const Unit& u, int wr, int wc, int fr, int fq) const {
;         const int row0 = u.pm * BM + wr * 64 + fr, col0 = u.pn * BM + wc * 32 + 8 * fq;
; #pragma unroll
;         for (int ai = 0; ai < 2; ++ai)
; #pragma unroll
;             for (int m = 0; m < 4; ++m) {
;                 const int row = row0 + ai * HALF + m * 16;
;                 float ss = 0.f;
; #pragma unroll
;                 for (int bj = 0; bj < 2; ++bj) {
;                     const size_t off = (size_t)row * DM + col0 + bj * HALF;
;                     f32x4 x0 = *(const f32x4*)(xin + off), x1 = *(const f32x4*)(xin + off + 4);
;                     x0 = x0 + acc[ai][bj][m][0] * scale; x1 = x1 + acc[ai][bj][m][1] * scale;
;                     ST_OUT2((f32x4*)(xout + off), x0); ST_OUT2((f32x4*)(xout + off + 4), x1);
;                     u32x4 o; o.x = pk2(x0[0], x0[1]); o.y = pk2(x0[2], x0[3]); o.z = pk2(x1[0], x1[1]); o.w = pk2(x1[2], x1[3]);
;                     if (wxb) ST_OUT2((u32x4*)(XB + off), o);
;                     ss += x0[0] * x0[0] + x0[1] * x0[1] + x0[2] * x0[2] + x0[3] * x0[3] + x1[0] * x1[0] + x1[1] * x1[1] + x1[2] * x1[2] + x1[3] * x1[3];
;                 }
;                 ss += __shfl_xor(ss, 16); ss += __shfl_xor(ss, 32);
;                 if (fq == 0) atomicAdd(rssn + row, (unsigned long long)(ss * 16777216.f));
	v_pk_fma_f32 v[100:101], v[100:101], 0.5, v[230:231] op_sel_hi:[1,0,1]
	v_pk_fma_f32 v[102:103], v[102:103], 0.5, v[232:233] op_sel_hi:[1,0,1]
	v_pk_fma_f32 v[96:97], v[96:97], 0.5, v[234:235] op_sel_hi:[1,0,1]
	v_pk_fma_f32 v[98:99], v[98:99], 0.5, v[236:237] op_sel_hi:[1,0,1]
	s_mov_b32 s100, 0x20000
	v_lshl_add_u64 v[182:183], v[196:197], 0, s[100:101]
	global_store_dwordx4 v[182:183], v[100:103], off offset:512
	global_store_dwordx4 v[182:183], v[96:99], off offset:528
	v_mul_f32_e32 v171, v101, v101
	v_fmac_f32_e32 v171, v100, v100
	v_fmac_f32_e32 v171, v102, v102
	v_fmac_f32_e32 v171, v103, v103
	v_fmac_f32_e32 v171, v96, v96
	v_fmac_f32_e32 v171, v97, v97
	v_fmac_f32_e32 v171, v98, v98
	v_fmac_f32_e32 v171, v99, v99
	v_add_f32_e32 v170, v170, v171
	ds_bpermute_b32 v163, v202, v170
	s_waitcnt lgkmcnt(0)
	v_add_f32_e32 v170, v170, v163
	ds_bpermute_b32 v163, v203, v170
	s_and_saveexec_b64 s[54:55], s[38:39]
	s_waitcnt lgkmcnt(0)
	v_add_f32_e32 v170, v170, v163
	v_mul_f32_e32 v170, 0x4b800000, v170
	v_trunc_f32_e32 v170, v170
	v_mul_f32_e32 v163, 0x2f800000, v170
	v_floor_f32_e32 v163, v163
	v_fmac_f32_e32 v170, 0xcf800000, v163
	v_cvt_u32_f32_e32 v172, v170
	v_cvt_u32_f32_e32 v173, v163
	s_mov_b32 s100, 0x80
	v_lshl_add_u64 v[184:185], v[200:201], 0, s[100:101]
	global_atomic_add_x2 v[184:185], v[172:173], off
	s_or_b64 exec, exec, s[54:55]
	s_mov_b32 s100, 0x60000
	v_lshl_add_u64 v[204:205], v[194:195], 0, s[100:101]
	global_load_dwordx4 v[230:233], v[204:205], off offset:512
	global_load_dwordx4 v[234:237], v[204:205], off offset:528
	s_waitcnt vmcnt(12)
	v_pk_fma_f32 v[92:93], v[92:93], 0.5, v[206:207] op_sel_hi:[1,0,1]
	v_pk_fma_f32 v[94:95], v[94:95], 0.5, v[208:209] op_sel_hi:[1,0,1]
	v_pk_fma_f32 v[88:89], v[88:89], 0.5, v[210:211] op_sel_hi:[1,0,1]
	v_pk_fma_f32 v[90:91], v[90:91], 0.5, v[212:213] op_sel_hi:[1,0,1]
	s_mov_b32 s100, 0x40000
	v_lshl_add_u64 v[182:183], v[196:197], 0, s[100:101]
	global_store_dwordx4 v[182:183], v[92:95], off
	global_store_dwordx4 v[182:183], v[88:91], off offset:16
	v_mul_f32_e32 v170, v93, v93
	v_fmac_f32_e32 v170, v92, v92
	v_fmac_f32_e32 v170, v94, v94
	v_fmac_f32_e32 v170, v95, v95
	v_fmac_f32_e32 v170, v88, v88
	v_fmac_f32_e32 v170, v89, v89
	v_fmac_f32_e32 v170, v90, v90
	v_fmac_f32_e32 v170, v91, v91
	s_mov_b32 s100, 0x100000
	v_lshl_add_u64 v[204:205], v[194:195], 0, s[100:101]
	global_load_dwordx4 v[206:209], v[204:205], off
	global_load_dwordx4 v[210:213], v[204:205], off offset:16
	s_waitcnt vmcnt(12)
	v_pk_fma_f32 v[84:85], v[84:85], 0.5, v[214:215] op_sel_hi:[1,0,1]
	v_pk_fma_f32 v[86:87], v[86:87], 0.5, v[216:217] op_sel_hi:[1,0,1]
	v_pk_fma_f32 v[80:81], v[80:81], 0.5, v[218:219] op_sel_hi:[1,0,1]
	v_pk_fma_f32 v[82:83], v[82:83], 0.5, v[220:221] op_sel_hi:[1,0,1]
	s_mov_b32 s100, 0x40000
	v_lshl_add_u64 v[182:183], v[196:197], 0, s[100:101]
	global_store_dwordx4 v[182:183], v[84:87], off offset:512
	global_store_dwordx4 v[182:183], v[80:83], off offset:528
	v_mul_f32_e32 v171, v85, v85
	v_fmac_f32_e32 v171, v84, v84
	v_fmac_f32_e32 v171, v86, v86
	v_fmac_f32_e32 v171, v87, v87
	v_fmac_f32_e32 v171, v80, v80
	v_fmac_f32_e32 v171, v81, v81
	v_fmac_f32_e32 v171, v82, v82
	v_fmac_f32_e32 v171, v83, v83
	v_add_f32_e32 v170, v170, v171
	ds_bpermute_b32 v163, v202, v170
	s_waitcnt lgkmcnt(0)
	v_add_f32_e32 v170, v170, v163
	ds_bpermute_b32 v163, v203, v170
	s_and_saveexec_b64 s[54:55], s[38:39]
	s_waitcnt lgkmcnt(0)
	v_add_f32_e32 v170, v170, v163
	v_mul_f32_e32 v170, 0x4b800000, v170
	v_trunc_f32_e32 v170, v170
	v_mul_f32_e32 v163, 0x2f800000, v170
	v_floor_f32_e32 v163, v163
	v_fmac_f32_e32 v170, 0xcf800000, v163
	v_cvt_u32_f32_e32 v172, v170
	v_cvt_u32_f32_e32 v173, v163
	s_mov_b32 s100, 0x100
	v_lshl_add_u64 v[184:185], v[200:201], 0, s[100:101]
	global_atomic_add_x2 v[184:185], v[172:173], off
	s_or_b64 exec, exec, s[54:55]
	s_mov_b32 s100, 0x100000
	v_lshl_add_u64 v[204:205], v[194:195], 0, s[100:101]
	global_load_dwordx4 v[214:217], v[204:205], off offset:512
	global_load_dwordx4 v[218:221], v[204:205], off offset:528
	s_waitcnt vmcnt(12)
	v_pk_fma_f32 v[76:77], v[76:77], 0.5, v[222:223] op_sel_hi:[1,0,1]
	v_pk_fma_f32 v[78:79], v[78:79], 0.5, v[224:225] op_sel_hi:[1,0,1]
	v_pk_fma_f32 v[72:73], v[72:73], 0.5, v[226:227] op_sel_hi:[1,0,1]
	v_pk_fma_f32 v[74:75], v[74:75], 0.5, v[228:229] op_sel_hi:[1,0,1]
	s_mov_b32 s100, 0x60000
	v_lshl_add_u64 v[182:183], v[196:197], 0, s[100:101]
	global_store_dwordx4 v[182:183], v[76:79], off
	global_store_dwordx4 v[182:183], v[72:75], off offset:16
	v_mul_f32_e32 v170, v77, v77
	v_fmac_f32_e32 v170, v76, v76
	v_fmac_f32_e32 v170, v78, v78
	v_fmac_f32_e32 v170, v79, v79
	v_fmac_f32_e32 v170, v72, v72
	v_fmac_f32_e32 v170, v73, v73
	v_fmac_f32_e32 v170, v74, v74
	v_fmac_f32_e32 v170, v75, v75
	s_mov_b32 s100, 0x120000
	v_lshl_add_u64 v[204:205], v[194:195], 0, s[100:101]
	global_load_dwordx4 v[222:225], v[204:205], off
	global_load_dwordx4 v[226:229], v[204:205], off offset:16
	s_waitcnt vmcnt(12)
	v_pk_fma_f32 v[68:69], v[68:69], 0.5, v[230:231] op_sel_hi:[1,0,1]
	v_pk_fma_f32 v[70:71], v[70:71], 0.5, v[232:233] op_sel_hi:[1,0,1]
	v_pk_fma_f32 v[64:65], v[64:65], 0.5, v[234:235] op_sel_hi:[1,0,1]
	v_pk_fma_f32 v[66:67], v[66:67], 0.5, v[236:237] op_sel_hi:[1,0,1]
	s_mov_b32 s100, 0x60000
	v_lshl_add_u64 v[182:183], v[196:197], 0, s[100:101]
	global_store_dwordx4 v[182:183], v[68:71], off offset:512
	global_store_dwordx4 v[182:183], v[64:67], off offset:528
	v_mul_f32_e32 v171, v69, v69
	v_fmac_f32_e32 v171, v68, v68
	v_fmac_f32_e32 v171, v70, v70
	v_fmac_f32_e32 v171, v71, v71
	v_fmac_f32_e32 v171, v64, v64
	v_fmac_f32_e32 v171, v65, v65
	v_fmac_f32_e32 v171, v66, v66
	v_fmac_f32_e32 v171, v67, v67
	v_add_f32_e32 v170, v170, v171
	ds_bpermute_b32 v163, v202, v170
	s_waitcnt lgkmcnt(0)
; __device__ __forceinline__ unsigned pk2(float lo, float hi) { const f32v2_t v = {lo, hi}; const bf16v2_t b = __builtin_convertvector(v, bf16v2_t); return __builtin_bit_cast(unsigned, b); }
; #define ST_OUT2(p, v) __builtin_nontemporal_store((v), (p))
;     __device__ __forceinline__ void operator()(AccRef acc, const Unit& u, int wr, int wc, int fr, int fq) const {
;         const int row0 = u.pm * BM + wr * 64 + fr, col0 = u.pn * BM + wc * 32 + 8 * fq;
; #pragma unroll
;         for (int ai = 0; ai < 2; ++ai)
; #pragma unroll
;             for (int m = 0; m < 4; ++m) {
;                 const int row = row0 + ai * HALF + m * 16;
;                 float ss = 0.f;
; #pragma unroll
;                 for (int bj = 0; bj < 2; ++bj) {
;                     const size_t off = (size_t)row * DM + col0 + bj * HALF;
;                     f32x4 x0 = *(const f32x4*)(xin + off), x1 = *(const f32x4*)(xin + off + 4);
;                     x0 = x0 + acc[ai][bj][m][0] * scale; x1 = x1 + acc[ai][bj][m][1] * scale;
;                     ST_OUT2((f32x4*)(xout + off), x0); ST_OUT2((f32x4*)(xout + off + 4), x1);
;                     u32x4 o; o.x = pk2(x0[0], x0[1]); o.y = pk2(x0[2], x0[3]); o.z = pk2(x1[0], x1[1]); o.w = pk2(x1[2], x1[3]);
;                     if (wxb) ST_OUT2((u32x4*)(XB + off), o);
;                     ss += x0[0] * x0[0] + x0[1] * x0[1] + x0[2] * x0[2] + x0[3] * x0[3] + x1[0] * x1[0] + x1[1] * x1[1] + x1[2] * x1[2] + x1[3] * x1[3];
;                 }
;                 ss += __shfl_xor(ss, 16); ss += __shfl_xor(ss, 32);
;                 if (fq == 0) atomicAdd(rssn + row, (unsigned long long)(ss * 16777216.f));
	v_add_f32_e32 v170, v170, v163
	ds_bpermute_b32 v163, v203, v170
	s_and_saveexec_b64 s[54:55], s[38:39]
	s_waitcnt lgkmcnt(0)
	v_add_f32_e32 v170, v170, v163
	v_mul_f32_e32 v170, 0x4b800000, v170
	v_trunc_f32_e32 v170, v170
	v_mul_f32_e32 v163, 0x2f800000, v170
	v_floor_f32_e32 v163, v163
	v_fmac_f32_e32 v170, 0xcf800000, v163
	v_cvt_u32_f32_e32 v172, v170
	v_cvt_u32_f32_e32 v173, v163
	s_mov_b32 s100, 0x180
	v_lshl_add_u64 v[184:185], v[200:201], 0, s[100:101]
	global_atomic_add_x2 v[184:185], v[172:173], off
	s_or_b64 exec, exec, s[54:55]
	s_mov_b32 s100, 0x120000
	v_lshl_add_u64 v[204:205], v[194:195], 0, s[100:101]
	global_load_dwordx4 v[230:233], v[204:205], off offset:512
	global_load_dwordx4 v[234:237], v[204:205], off offset:528
	s_waitcnt vmcnt(12)
	v_pk_fma_f32 v[60:61], v[60:61], 0.5, v[206:207] op_sel_hi:[1,0,1]
	v_pk_fma_f32 v[62:63], v[62:63], 0.5, v[208:209] op_sel_hi:[1,0,1]
	v_pk_fma_f32 v[56:57], v[56:57], 0.5, v[210:211] op_sel_hi:[1,0,1]
	v_pk_fma_f32 v[58:59], v[58:59], 0.5, v[212:213] op_sel_hi:[1,0,1]
	s_mov_b32 s100, 0x100000
	v_lshl_add_u64 v[182:183], v[196:197], 0, s[100:101]
	global_store_dwordx4 v[182:183], v[60:63], off
	global_store_dwordx4 v[182:183], v[56:59], off offset:16
	v_mul_f32_e32 v170, v61, v61
	v_fmac_f32_e32 v170, v60, v60
	v_fmac_f32_e32 v170, v62, v62
	v_fmac_f32_e32 v170, v63, v63
	v_fmac_f32_e32 v170, v56, v56
	v_fmac_f32_e32 v170, v57, v57
	v_fmac_f32_e32 v170, v58, v58
	v_fmac_f32_e32 v170, v59, v59
	s_mov_b32 s100, 0x140000
	v_lshl_add_u64 v[204:205], v[194:195], 0, s[100:101]
	global_load_dwordx4 v[206:209], v[204:205], off
	global_load_dwordx4 v[210:213], v[204:205], off offset:16
	s_waitcnt vmcnt(12)
	v_pk_fma_f32 v[52:53], v[52:53], 0.5, v[214:215] op_sel_hi:[1,0,1]
	v_pk_fma_f32 v[54:55], v[54:55], 0.5, v[216:217] op_sel_hi:[1,0,1]
	v_pk_fma_f32 v[48:49], v[48:49], 0.5, v[218:219] op_sel_hi:[1,0,1]
	v_pk_fma_f32 v[50:51], v[50:51], 0.5, v[220:221] op_sel_hi:[1,0,1]
	s_mov_b32 s100, 0x100000
	v_lshl_add_u64 v[182:183], v[196:197], 0, s[100:101]
	global_store_dwordx4 v[182:183], v[52:55], off offset:512
	global_store_dwordx4 v[182:183], v[48:51], off offset:528
	v_mul_f32_e32 v171, v53, v53
	v_fmac_f32_e32 v171, v52, v52
	v_fmac_f32_e32 v171, v54, v54
	v_fmac_f32_e32 v171, v55, v55
	v_fmac_f32_e32 v171, v48, v48
	v_fmac_f32_e32 v171, v49, v49
	v_fmac_f32_e32 v171, v50, v50
	v_fmac_f32_e32 v171, v51, v51
	v_add_f32_e32 v170, v170, v171
	ds_bpermute_b32 v163, v202, v170
	s_waitcnt lgkmcnt(0)
	v_add_f32_e32 v170, v170, v163
	ds_bpermute_b32 v163, v203, v170
	s_and_saveexec_b64 s[54:55], s[38:39]
	s_waitcnt lgkmcnt(0)
	v_add_f32_e32 v170, v170, v163
	v_mul_f32_e32 v170, 0x4b800000, v170
	v_trunc_f32_e32 v170, v170
	v_mul_f32_e32 v163, 0x2f800000, v170
	v_floor_f32_e32 v163, v163
	v_fmac_f32_e32 v170, 0xcf800000, v163
	v_cvt_u32_f32_e32 v172, v170
	v_cvt_u32_f32_e32 v173, v163
	s_mov_b32 s100, 0x400
	v_lshl_add_u64 v[184:185], v[200:201], 0, s[100:101]
	global_atomic_add_x2 v[184:185], v[172:173], off
	s_or_b64 exec, exec, s[54:55]
	s_mov_b32 s100, 0x140000
	v_lshl_add_u64 v[204:205], v[194:195], 0, s[100:101]
	global_load_dwordx4 v[214:217], v[204:205], off offset:512
	global_load_dwordx4 v[218:221], v[204:205], off offset:528
	s_waitcnt vmcnt(12)
	v_pk_fma_f32 v[44:45], v[44:45], 0.5, v[222:223] op_sel_hi:[1,0,1]
	v_pk_fma_f32 v[46:47], v[46:47], 0.5, v[224:225] op_sel_hi:[1,0,1]
	v_pk_fma_f32 v[40:41], v[40:41], 0.5, v[226:227] op_sel_hi:[1,0,1]
	v_pk_fma_f32 v[42:43], v[42:43], 0.5, v[228:229] op_sel_hi:[1,0,1]
	s_mov_b32 s100, 0x120000
	v_lshl_add_u64 v[182:183], v[196:197], 0, s[100:101]
	global_store_dwordx4 v[182:183], v[44:47], off
	global_store_dwordx4 v[182:183], v[40:43], off offset:16
	v_mul_f32_e32 v170, v45, v45
	v_fmac_f32_e32 v170, v44, v44
	v_fmac_f32_e32 v170, v46, v46
	v_fmac_f32_e32 v170, v47, v47
	v_fmac_f32_e32 v170, v40, v40
	v_fmac_f32_e32 v170, v41, v41
	v_fmac_f32_e32 v170, v42, v42
	v_fmac_f32_e32 v170, v43, v43
	s_mov_b32 s100, 0x160000
	v_lshl_add_u64 v[204:205], v[194:195], 0, s[100:101]
	global_load_dwordx4 v[222:225], v[204:205], off
	global_load_dwordx4 v[226:229], v[204:205], off offset:16
	s_waitcnt vmcnt(12)
	v_pk_fma_f32 v[36:37], v[36:37], 0.5, v[230:231] op_sel_hi:[1,0,1]
	v_pk_fma_f32 v[38:39], v[38:39], 0.5, v[232:233] op_sel_hi:[1,0,1]
	v_pk_fma_f32 v[32:33], v[32:33], 0.5, v[234:235] op_sel_hi:[1,0,1]
	v_pk_fma_f32 v[34:35], v[34:35], 0.5, v[236:237] op_sel_hi:[1,0,1]
	s_mov_b32 s100, 0x120000
	v_lshl_add_u64 v[182:183], v[196:197], 0, s[100:101]
	global_store_dwordx4 v[182:183], v[36:39], off offset:512
	global_store_dwordx4 v[182:183], v[32:35], off offset:528
	v_mul_f32_e32 v171, v37, v37
	v_fmac_f32_e32 v171, v36, v36
	v_fmac_f32_e32 v171, v38, v38
	v_fmac_f32_e32 v171, v39, v39
	v_fmac_f32_e32 v171, v32, v32
	v_fmac_f32_e32 v171, v33, v33
	v_fmac_f32_e32 v171, v34, v34
	v_fmac_f32_e32 v171, v35, v35
	v_add_f32_e32 v170, v170, v171
	ds_bpermute_b32 v163, v202, v170
	s_waitcnt lgkmcnt(0)
; __device__ __forceinline__ unsigned pk2(float lo, float hi) { const f32v2_t v = {lo, hi}; const bf16v2_t b = __builtin_convertvector(v, bf16v2_t); return __builtin_bit_cast(unsigned, b); }
; #define ST_OUT2(p, v) __builtin_nontemporal_store((v), (p))
;     __device__ __forceinline__ void operator()(AccRef acc, const Unit& u, int wr, int wc, int fr, int fq) const {
;         const int row0 = u.pm * BM + wr * 64 + fr, col0 = u.pn * BM + wc * 32 + 8 * fq;
; #pragma unroll
;         for (int ai = 0; ai < 2; ++ai)
; #pragma unroll
;             for (int m = 0; m < 4; ++m) {
;                 const int row = row0 + ai * HALF + m * 16;
;                 float ss = 0.f;
; #pragma unroll
;                 for (int bj = 0; bj < 2; ++bj) {
;                     const size_t off = (size_t)row * DM + col0 + bj * HALF;
;                     f32x4 x0 = *(const f32x4*)(xin + off), x1 = *(const f32x4*)(xin + off + 4);
;                     x0 = x0 + acc[ai][bj][m][0] * scale; x1 = x1 + acc[ai][bj][m][1] * scale;
;                     ST_OUT2((f32x4*)(xout + off), x0); ST_OUT2((f32x4*)(xout + off + 4), x1);
;                     u32x4 o; o.x = pk2(x0[0], x0[1]); o.y = pk2(x0[2], x0[3]); o.z = pk2(x1[0], x1[1]); o.w = pk2(x1[2], x1[3]);
;                     if (wxb) ST_OUT2((u32x4*)(XB + off), o);
;                     ss += x0[0] * x0[0] + x0[1] * x0[1] + x0[2] * x0[2] + x0[3] * x0[3] + x1[0] * x1[0] + x1[1] * x1[1] + x1[2] * x1[2] + x1[3] * x1[3];
;                 }
;                 ss += __shfl_xor(ss, 16); ss += __shfl_xor(ss, 32);
;                 if (fq == 0) atomicAdd(rssn + row, (unsigned long long)(ss * 16777216.f));
	v_add_f32_e32 v170, v170, v163
	ds_bpermute_b32 v163, v203, v170
	s_and_saveexec_b64 s[54:55], s[38:39]
	s_waitcnt lgkmcnt(0)
	v_add_f32_e32 v170, v170, v163
	v_mul_f32_e32 v170, 0x4b800000, v170
	v_trunc_f32_e32 v170, v170
	v_mul_f32_e32 v163, 0x2f800000, v170
	v_floor_f32_e32 v163, v163
	v_fmac_f32_e32 v170, 0xcf800000, v163
	v_cvt_u32_f32_e32 v172, v170
	v_cvt_u32_f32_e32 v173, v163
	s_mov_b32 s100, 0x480
	v_lshl_add_u64 v[184:185], v[200:201], 0, s[100:101]
	global_atomic_add_x2 v[184:185], v[172:173], off
	s_or_b64 exec, exec, s[54:55]
	s_mov_b32 s100, 0x160000
	v_lshl_add_u64 v[204:205], v[194:195], 0, s[100:101]
	global_load_dwordx4 v[230:233], v[204:205], off offset:512
	global_load_dwordx4 v[234:237], v[204:205], off offset:528
	s_waitcnt vmcnt(12)
	v_pk_fma_f32 v[28:29], v[28:29], 0.5, v[206:207] op_sel_hi:[1,0,1]
	v_pk_fma_f32 v[30:31], v[30:31], 0.5, v[208:209] op_sel_hi:[1,0,1]
	v_pk_fma_f32 v[24:25], v[24:25], 0.5, v[210:211] op_sel_hi:[1,0,1]
	v_pk_fma_f32 v[26:27], v[26:27], 0.5, v[212:213] op_sel_hi:[1,0,1]
	s_mov_b32 s100, 0x140000
	v_lshl_add_u64 v[182:183], v[196:197], 0, s[100:101]
	global_store_dwordx4 v[182:183], v[28:31], off
	global_store_dwordx4 v[182:183], v[24:27], off offset:16
	v_mul_f32_e32 v170, v29, v29
	v_fmac_f32_e32 v170, v28, v28
	v_fmac_f32_e32 v170, v30, v30
	v_fmac_f32_e32 v170, v31, v31
	v_fmac_f32_e32 v170, v24, v24
	v_fmac_f32_e32 v170, v25, v25
	v_fmac_f32_e32 v170, v26, v26
	v_fmac_f32_e32 v170, v27, v27
	s_waitcnt vmcnt(10)
	v_pk_fma_f32 v[20:21], v[20:21], 0.5, v[214:215] op_sel_hi:[1,0,1]
	v_pk_fma_f32 v[22:23], v[22:23], 0.5, v[216:217] op_sel_hi:[1,0,1]
	v_pk_fma_f32 v[16:17], v[16:17], 0.5, v[218:219] op_sel_hi:[1,0,1]
	v_pk_fma_f32 v[18:19], v[18:19], 0.5, v[220:221] op_sel_hi:[1,0,1]
	s_mov_b32 s100, 0x140000
	v_lshl_add_u64 v[182:183], v[196:197], 0, s[100:101]
	global_store_dwordx4 v[182:183], v[20:23], off offset:512
	global_store_dwordx4 v[182:183], v[16:19], off offset:528
	v_mul_f32_e32 v171, v21, v21
	v_fmac_f32_e32 v171, v20, v20
	v_fmac_f32_e32 v171, v22, v22
	v_fmac_f32_e32 v171, v23, v23
	v_fmac_f32_e32 v171, v16, v16
	v_fmac_f32_e32 v171, v17, v17
	v_fmac_f32_e32 v171, v18, v18
	v_fmac_f32_e32 v171, v19, v19
	v_add_f32_e32 v170, v170, v171
	ds_bpermute_b32 v163, v202, v170
	s_waitcnt lgkmcnt(0)
	v_add_f32_e32 v170, v170, v163
	ds_bpermute_b32 v163, v203, v170
	s_and_saveexec_b64 s[54:55], s[38:39]
	s_waitcnt lgkmcnt(0)
	v_add_f32_e32 v170, v170, v163
	v_mul_f32_e32 v170, 0x4b800000, v170
	v_trunc_f32_e32 v170, v170
	v_mul_f32_e32 v163, 0x2f800000, v170
	v_floor_f32_e32 v163, v163
	v_fmac_f32_e32 v170, 0xcf800000, v163
	v_cvt_u32_f32_e32 v172, v170
	v_cvt_u32_f32_e32 v173, v163
	s_mov_b32 s100, 0x500
	v_lshl_add_u64 v[184:185], v[200:201], 0, s[100:101]
	global_atomic_add_x2 v[184:185], v[172:173], off
	s_or_b64 exec, exec, s[54:55]
	s_waitcnt vmcnt(8)
	v_pk_fma_f32 v[12:13], v[12:13], 0.5, v[222:223] op_sel_hi:[1,0,1]
	v_pk_fma_f32 v[14:15], v[14:15], 0.5, v[224:225] op_sel_hi:[1,0,1]
	v_pk_fma_f32 v[8:9], v[8:9], 0.5, v[226:227] op_sel_hi:[1,0,1]
	v_pk_fma_f32 v[10:11], v[10:11], 0.5, v[228:229] op_sel_hi:[1,0,1]
	s_mov_b32 s100, 0x160000
	v_lshl_add_u64 v[182:183], v[196:197], 0, s[100:101]
	global_store_dwordx4 v[182:183], v[12:15], off
	global_store_dwordx4 v[182:183], v[8:11], off offset:16
	v_mul_f32_e32 v170, v13, v13
	v_fmac_f32_e32 v170, v12, v12
	v_fmac_f32_e32 v170, v14, v14
	v_fmac_f32_e32 v170, v15, v15
	v_fmac_f32_e32 v170, v8, v8
	v_fmac_f32_e32 v170, v9, v9
	v_fmac_f32_e32 v170, v10, v10
	v_fmac_f32_e32 v170, v11, v11
	s_waitcnt vmcnt(6)
	v_pk_fma_f32 v[4:5], v[4:5], 0.5, v[230:231] op_sel_hi:[1,0,1]
	v_pk_fma_f32 v[6:7], v[6:7], 0.5, v[232:233] op_sel_hi:[1,0,1]
	v_pk_fma_f32 v[0:1], v[0:1], 0.5, v[234:235] op_sel_hi:[1,0,1]
	v_pk_fma_f32 v[2:3], v[2:3], 0.5, v[236:237] op_sel_hi:[1,0,1]
	s_mov_b32 s100, 0x160000
	v_lshl_add_u64 v[182:183], v[196:197], 0, s[100:101]
	global_store_dwordx4 v[182:183], v[4:7], off offset:512
	global_store_dwordx4 v[182:183], v[0:3], off offset:528
	v_mul_f32_e32 v171, v5, v5
	v_fmac_f32_e32 v171, v4, v4
	v_fmac_f32_e32 v171, v6, v6
	v_fmac_f32_e32 v171, v7, v7
	v_fmac_f32_e32 v171, v0, v0
	v_fmac_f32_e32 v171, v1, v1
	v_fmac_f32_e32 v171, v2, v2
	v_fmac_f32_e32 v171, v3, v3
	v_add_f32_e32 v170, v170, v171
	ds_bpermute_b32 v163, v202, v170
	s_waitcnt lgkmcnt(0)
	v_add_f32_e32 v170, v170, v163
	ds_bpermute_b32 v163, v203, v170
	s_and_saveexec_b64 s[54:55], s[38:39]
	s_waitcnt lgkmcnt(0)
	v_add_f32_e32 v170, v170, v163
	v_mul_f32_e32 v170, 0x4b800000, v170
	v_trunc_f32_e32 v170, v170
	v_mul_f32_e32 v163, 0x2f800000, v170
	v_floor_f32_e32 v163, v163
	v_fmac_f32_e32 v170, 0xcf800000, v163
	v_cvt_u32_f32_e32 v172, v170
	v_cvt_u32_f32_e32 v173, v163
	s_mov_b32 s100, 0x580
	v_lshl_add_u64 v[184:185], v[200:201], 0, s[100:101]
	global_atomic_add_x2 v[184:185], v[172:173], off
	s_or_b64 exec, exec, s[54:55]
